# GLA pre-pass: the q_inter image stores (full-line dword stores, read once by the scan in the next phase) marked non-temporal
# speedup vs baseline: 1.0018x; 1.0018x over previous
.LBB0_286:
	s_and_b32 s13, s53, 1
	s_xor_b32 s11, s0, 31
	s_cmp_eq_u32 s13, 0
	s_cselect_b64 s[14:15], -1, 0
	s_and_b64 s[14:15], s[14:15], exec
	s_cselect_b32 s0, s0, s11
	s_lshl_b32 s11, s0, 6
	s_xor_b32 s12, s11, 0x7ff
	s_cmp_eq_u32 s13, 0
	s_cselect_b64 vcc, -1, 0
	s_and_b64 s[14:15], vcc, exec
	s_movk_i32 s14, 0x5040
	s_cselect_b32 s14, s14, 0xffffafc0
	s_cselect_b32 s11, s11, s12
	s_lshl_b32 s10, s10, 3
	s_and_b32 s12, s53, 6
	s_or_b32 s10, s10, s12
	s_waitcnt vmcnt(4)
	v_mov_b32_e32 v0, v65
	s_or_b32 s10, s10, s13
	s_or_b32 s3, s11, s3
	s_lshl_b32 s12, s10, 5
	v_add_u32_e32 v82, v0, v190
	s_mul_hi_i32 s11, s3, 0xa080
	s_mul_i32 s3, s3, 0xa080
	v_ashrrev_i32_e32 v123, 7, v82
	s_add_u32 s10, s24, s3
	v_and_b32_e32 v127, 0x7f, v82
	s_addc_u32 s11, s25, s11
	s_lshl_b32 s2, s2, 7
	v_lshlrev_b32_e32 v104, 4, v123
	s_and_b32 s15, s2, 0x300
	v_lshlrev_b32_e32 v0, 1, v127
	v_mul_lo_u32 v1, v104, s14
	v_or3_b32 v0, s15, v0, v1
	v_add_u32_e32 v0, 0x1800, v0
	v_ashrrev_i32_e32 v1, 31, v0
	v_lshl_add_u64 v[2:3], v[0:1], 1, s[10:11]
	v_add_u32_e32 v0, s14, v0
	v_ashrrev_i32_e32 v1, 31, v0
	global_load_dword v132, v[2:3], off
	global_load_dword v131, v[2:3], off offset:2048
	v_lshl_add_u64 v[2:3], v[0:1], 1, s[10:11]
	v_add_u32_e32 v0, s14, v0
	v_ashrrev_i32_e32 v1, 31, v0
	global_load_dword v130, v[2:3], off
	global_load_dword v129, v[2:3], off offset:2048
	v_lshl_add_u64 v[2:3], v[0:1], 1, s[10:11]
	v_add_u32_e32 v0, s14, v0
	v_ashrrev_i32_e32 v1, 31, v0
	global_load_dword v126, v[2:3], off
	global_load_dword v125, v[2:3], off offset:2048
	v_lshl_add_u64 v[2:3], v[0:1], 1, s[10:11]
	v_add_u32_e32 v0, s14, v0
	v_ashrrev_i32_e32 v1, 31, v0
	global_load_dword v122, v[2:3], off
	global_load_dword v121, v[2:3], off offset:2048
	v_lshl_add_u64 v[2:3], v[0:1], 1, s[10:11]
	v_add_u32_e32 v0, s14, v0
	v_ashrrev_i32_e32 v1, 31, v0
	global_load_dword v119, v[2:3], off
	global_load_dword v118, v[2:3], off offset:2048
	v_lshl_add_u64 v[2:3], v[0:1], 1, s[10:11]
	v_add_u32_e32 v0, s14, v0
	v_ashrrev_i32_e32 v1, 31, v0
	global_load_dword v116, v[2:3], off
	global_load_dword v115, v[2:3], off offset:2048
	v_lshl_add_u64 v[2:3], v[0:1], 1, s[10:11]
	v_add_u32_e32 v0, s14, v0
	v_ashrrev_i32_e32 v1, 31, v0
	global_load_dword v113, v[2:3], off
	global_load_dword v112, v[2:3], off offset:2048
	v_lshl_add_u64 v[2:3], v[0:1], 1, s[10:11]
	v_add_u32_e32 v0, s14, v0
	v_ashrrev_i32_e32 v1, 31, v0
	global_load_dword v110, v[2:3], off
	global_load_dword v109, v[2:3], off offset:2048
	v_lshl_add_u64 v[2:3], v[0:1], 1, s[10:11]
	v_add_u32_e32 v0, s14, v0
	v_ashrrev_i32_e32 v1, 31, v0
	global_load_dword v107, v[2:3], off
	global_load_dword v106, v[2:3], off offset:2048
	v_lshl_add_u64 v[2:3], v[0:1], 1, s[10:11]
	v_add_u32_e32 v0, s14, v0
	v_ashrrev_i32_e32 v1, 31, v0
	global_load_dword v103, v[2:3], off
	global_load_dword v102, v[2:3], off offset:2048
	v_lshl_add_u64 v[2:3], v[0:1], 1, s[10:11]
	v_add_u32_e32 v0, s14, v0
	v_ashrrev_i32_e32 v1, 31, v0
	global_load_dword v100, v[2:3], off
	global_load_dword v99, v[2:3], off offset:2048
	v_lshl_add_u64 v[2:3], v[0:1], 1, s[10:11]
	v_add_u32_e32 v0, s14, v0
	v_ashrrev_i32_e32 v1, 31, v0
	global_load_dword v97, v[2:3], off
	global_load_dword v96, v[2:3], off offset:2048
	v_lshl_add_u64 v[2:3], v[0:1], 1, s[10:11]
	v_add_u32_e32 v0, s14, v0
	v_ashrrev_i32_e32 v1, 31, v0
	global_load_dword v94, v[2:3], off
	global_load_dword v93, v[2:3], off offset:2048
	v_lshl_add_u64 v[2:3], v[0:1], 1, s[10:11]
	v_add_u32_e32 v0, s14, v0
	v_ashrrev_i32_e32 v1, 31, v0
	global_load_dword v91, v[2:3], off
	global_load_dword v90, v[2:3], off offset:2048
	v_lshl_add_u64 v[2:3], v[0:1], 1, s[10:11]
	v_add_u32_e32 v0, s14, v0
	s_or_b32 s2, s13, s22
	v_ashrrev_i32_e32 v1, 31, v0
	s_ashr_i32 s3, s2, 31
	v_readlane_b32 s72, v252, 9
	v_lshl_add_u64 v[0:1], v[0:1], 1, s[10:11]
	s_lshl_b64 s[10:11], s[2:3], 16
	v_readlane_b32 s86, v252, 23
	v_readlane_b32 s87, v252, 24
	s_add_u32 s10, s86, s10
	s_addc_u32 s11, s87, s11
	s_lshl_b32 s14, s15, 2
	s_add_u32 s10, s10, s14
	s_addc_u32 s11, s11, 0
	v_lshlrev_b32_e32 v64, 3, v127
	global_load_dword v88, v[2:3], off
	global_load_dword v87, v[2:3], off offset:2048
	global_load_dword v85, v[0:1], off
	global_load_dword v84, v[0:1], off offset:2048
	v_lshl_add_u64 v[0:1], s[10:11], 0, v[64:65]
	global_load_dwordx2 v[30:31], v64, s[10:11]
	s_movk_i32 s10, 0x2000
	v_add_co_u32_e64 v2, s[62:63], s10, v0
	s_movk_i32 s10, 0x4000
	s_nop 0
	v_addc_co_u32_e64 v3, s[62:63], 0, v1, s[62:63]
	global_load_dwordx2 v[32:33], v[2:3], off offset:-4096
	global_load_dwordx2 v[26:27], v[2:3], off
	v_add_co_u32_e64 v2, s[62:63], s10, v0
	s_movk_i32 s10, 0x6000
	s_nop 0
	v_addc_co_u32_e64 v3, s[62:63], 0, v1, s[62:63]
	global_load_dwordx2 v[28:29], v[2:3], off offset:-4096
	global_load_dwordx2 v[22:23], v[2:3], off
	v_add_co_u32_e64 v2, s[62:63], s10, v0
	s_mov_b32 s10, 0x8000
	s_nop 0
	v_addc_co_u32_e64 v3, s[62:63], 0, v1, s[62:63]
	global_load_dwordx2 v[24:25], v[2:3], off offset:-4096
	global_load_dwordx2 v[18:19], v[2:3], off
	v_add_co_u32_e64 v2, s[62:63], s10, v0
	s_mov_b32 s10, 0xc000
	s_nop 0
	v_addc_co_u32_e64 v3, s[62:63], 0, v1, s[62:63]
	global_load_dwordx2 v[20:21], v[2:3], off offset:-4096
	global_load_dwordx2 v[16:17], v[2:3], off
	v_add_co_u32_e64 v2, s[62:63], s89, v0
	v_readlane_b32 s73, v252, 10
	s_nop 0
	v_addc_co_u32_e64 v3, s[62:63], 0, v1, s[62:63]
	v_readlane_b32 s74, v252, 11
	v_readlane_b32 s75, v252, 12
	v_readlane_b32 s76, v252, 13
	v_readlane_b32 s77, v252, 14
	v_readlane_b32 s78, v252, 15
	v_readlane_b32 s79, v252, 16
	v_readlane_b32 s80, v252, 17
	v_readlane_b32 s81, v252, 18
	v_readlane_b32 s82, v252, 19
	v_readlane_b32 s83, v252, 20
	v_readlane_b32 s84, v252, 21
	v_readlane_b32 s85, v252, 22
	global_load_dwordx2 v[14:15], v[2:3], off offset:-4096
	global_load_dwordx2 v[10:11], v[2:3], off
	v_add_co_u32_e64 v2, s[62:63], s10, v0
	s_mov_b32 s10, 0xe000
	s_nop 0
	v_addc_co_u32_e64 v3, s[62:63], 0, v1, s[62:63]
	s_lshl_b64 s[2:3], s[2:3], 12
	v_readlane_b32 s72, v252, 25
	global_load_dwordx2 v[12:13], v[2:3], off offset:-4096
	global_load_dwordx2 v[8:9], v[2:3], off
	v_add_co_u32_e64 v2, s[62:63], s10, v0
	v_readlane_b32 s73, v252, 26
	s_add_u32 s2, s72, s2
	v_addc_co_u32_e64 v3, s[62:63], 0, v1, s[62:63]
	s_mov_b32 s10, 0xf000
	s_addc_u32 s3, s73, s3
	v_add_co_u32_e64 v0, s[62:63], s10, v0
	s_add_u32 s2, s2, s14
	s_nop 0
	v_addc_co_u32_e64 v1, s[62:63], 0, v1, s[62:63]
	s_addc_u32 s3, s3, 0
	global_load_dwordx2 v[6:7], v[2:3], off offset:-4096
	global_load_dwordx2 v[4:5], v[2:3], off
	v_sub_u32_e32 v34, 63, v104
	global_load_dwordx2 v[2:3], v[0:1], off
	v_cndmask_b32_e32 v34, v34, v104, vcc
	global_load_dwordx2 v[0:1], v64, s[2:3]
	s_lshl_b32 s2, s13, 6
	s_add_i32 s10, s2, 0
	s_add_i32 s10, s10, 0x19800
	s_waitcnt lgkmcnt(0)
	s_barrier
	v_lshl_add_u32 v46, v34, 7, s10
	ds_read_b128 v[34:37], v46
	ds_read_b128 v[38:41], v46 offset:16
	ds_read_b128 v[42:45], v46 offset:32
	ds_read_b128 v[46:49], v46 offset:48
	v_or_b32_e32 v128, 1, v104
	v_or_b32_e32 v124, 2, v104
	v_or_b32_e32 v120, 3, v104
	v_or_b32_e32 v117, 4, v104
	s_mov_b32 s2, 0x3d800000
	v_or_b32_e32 v114, 5, v104
	v_or_b32_e32 v111, 6, v104
	v_or_b32_e32 v108, 7, v104
	v_or_b32_e32 v105, 8, v104
	v_or_b32_e32 v101, 9, v104
	v_or_b32_e32 v98, 10, v104
	v_or_b32_e32 v95, 11, v104
	v_or_b32_e32 v92, 12, v104
	v_or_b32_e32 v89, 13, v104
	v_or_b32_e32 v86, 14, v104
	v_or_b32_e32 v83, 15, v104
	v_readlane_b32 s74, v252, 27
	v_readlane_b32 s75, v252, 28
	v_readlane_b32 s76, v252, 29
	v_readlane_b32 s77, v252, 30
	v_readlane_b32 s78, v252, 31
	v_readlane_b32 s79, v252, 32
	v_readlane_b32 s80, v252, 33
	v_readlane_b32 s81, v252, 34
	v_readlane_b32 s82, v252, 35
	v_readlane_b32 s83, v252, 36
	v_readlane_b32 s84, v252, 37
	v_readlane_b32 s85, v252, 38
	v_readlane_b32 s86, v252, 39
	v_readlane_b32 s87, v252, 40
	s_waitcnt vmcnt(0) lgkmcnt(3)
	v_fma_f32 v50, v34, v30, v0
	v_fmac_f32_e32 v50, v35, v32
	v_fmac_f32_e32 v50, v36, v26
	v_fmac_f32_e32 v50, v37, v28
	s_waitcnt lgkmcnt(2)
	v_fmac_f32_e32 v50, v38, v22
	v_fmac_f32_e32 v50, v39, v24
	v_fmac_f32_e32 v50, v40, v18
	v_fmac_f32_e32 v50, v41, v20
	s_waitcnt lgkmcnt(1)
	v_fmac_f32_e32 v50, v42, v16
	v_fmac_f32_e32 v50, v43, v14
	v_fmac_f32_e32 v50, v44, v10
	v_fma_f32 v51, v34, v31, v1
	v_fmac_f32_e32 v50, v45, v12
	v_fmac_f32_e32 v51, v35, v33
	s_waitcnt lgkmcnt(0)
	v_fmac_f32_e32 v50, v46, v8
	v_fmac_f32_e32 v51, v36, v27
	v_fmac_f32_e32 v50, v47, v6
	v_fmac_f32_e32 v51, v37, v29
	v_fmac_f32_e32 v50, v48, v4
	v_fmac_f32_e32 v51, v38, v23
	v_fmac_f32_e32 v50, v49, v2
	v_fmac_f32_e32 v51, v39, v25
	v_mul_f32_e64 v35, |v50|, s90
	v_fmac_f32_e32 v51, v40, v19
	v_exp_f32_e32 v35, v35
	v_fmac_f32_e32 v51, v41, v21
	v_fmac_f32_e32 v51, v42, v17
	v_fmac_f32_e32 v51, v43, v15
	v_fmac_f32_e32 v51, v44, v11
	v_add_f32_e32 v35, 1.0, v35
	v_fmac_f32_e32 v51, v45, v13
	v_cmp_gt_f32_e64 s[62:63], s92, v35
	v_fmac_f32_e32 v51, v46, v9
	v_fmac_f32_e32 v51, v47, v7
	v_cndmask_b32_e64 v36, 0, 32, s[62:63]
	v_ldexp_f32 v35, v35, v36
	v_fmac_f32_e32 v51, v48, v5
	v_log_f32_e32 v35, v35
	v_fmac_f32_e32 v51, v49, v3
	v_mul_f32_e64 v37, |v51|, s90
	v_exp_f32_e32 v37, v37
	v_mul_f32_e32 v36, 0x3f317217, v35
	v_fma_f32 v36, v35, s41, -v36
	v_fmac_f32_e32 v36, 0x3377d1cf, v35
	v_fmac_f32_e32 v36, 0x3f317217, v35
	v_cmp_lt_f32_e64 s[64:65], |v35|, s68
	v_add_f32_e32 v37, 1.0, v37
	v_min_f32_e32 v34, 0, v50
	v_cndmask_b32_e64 v35, v35, v36, s[64:65]
	v_cndmask_b32_e64 v36, 0, v187, s[62:63]
	v_cmp_gt_f32_e64 s[62:63], s92, v37
	v_sub_f32_e32 v36, v35, v36
	v_min_f32_e32 v35, 0, v51
	v_cndmask_b32_e64 v38, 0, 32, s[62:63]
	v_ldexp_f32 v37, v37, v38
	v_log_f32_e32 v37, v37
	s_nop 0
	v_mul_f32_e32 v38, 0x3f317217, v37
	v_fma_f32 v38, v37, s41, -v38
	v_fmac_f32_e32 v38, 0x3377d1cf, v37
	v_fmac_f32_e32 v38, 0x3f317217, v37
	v_cmp_lt_f32_e64 s[64:65], |v37|, s68
	s_nop 1
	v_cndmask_b32_e64 v37, v37, v38, s[64:65]
	v_cndmask_b32_e64 v38, 0, v187, s[62:63]
	v_sub_f32_e32 v37, v37, v38
	v_sub_u32_e32 v38, 63, v128
	v_cndmask_b32_e32 v38, v38, v128, vcc
	v_lshl_add_u32 v50, v38, 7, s10
	ds_read_b128 v[38:41], v50
	ds_read_b128 v[42:45], v50 offset:16
	ds_read_b128 v[46:49], v50 offset:32
	ds_read_b128 v[50:53], v50 offset:48
	v_pk_add_f32 v[34:35], v[34:35], v[36:37] neg_lo:[0,1] neg_hi:[0,1]
	s_waitcnt lgkmcnt(3)
	v_fma_f32 v54, v38, v30, v0
	v_fmac_f32_e32 v54, v39, v32
	v_fmac_f32_e32 v54, v40, v26
	v_fmac_f32_e32 v54, v41, v28
	s_waitcnt lgkmcnt(2)
	v_fmac_f32_e32 v54, v42, v22
	v_fmac_f32_e32 v54, v43, v24
	v_fmac_f32_e32 v54, v44, v18
	v_fmac_f32_e32 v54, v45, v20
	s_waitcnt lgkmcnt(1)
	v_fmac_f32_e32 v54, v46, v16
	v_fmac_f32_e32 v54, v47, v14
	v_fmac_f32_e32 v54, v48, v10
	v_fma_f32 v55, v38, v31, v1
	v_fmac_f32_e32 v54, v49, v12
	v_fmac_f32_e32 v55, v39, v33
	s_waitcnt lgkmcnt(0)
	v_fmac_f32_e32 v54, v50, v8
	v_fmac_f32_e32 v55, v40, v27
	v_fmac_f32_e32 v54, v51, v6
	v_fmac_f32_e32 v55, v41, v29
	v_fmac_f32_e32 v54, v52, v4
	v_fmac_f32_e32 v55, v42, v23
	v_fmac_f32_e32 v54, v53, v2
	v_fmac_f32_e32 v55, v43, v25
	v_mul_f32_e64 v39, |v54|, s90
	v_fmac_f32_e32 v55, v44, v19
	v_exp_f32_e32 v39, v39
	v_fmac_f32_e32 v55, v45, v21
	v_fmac_f32_e32 v55, v46, v17
	v_fmac_f32_e32 v55, v47, v15
	v_fmac_f32_e32 v55, v48, v11
	v_add_f32_e32 v39, 1.0, v39
	v_fmac_f32_e32 v55, v49, v13
	v_cmp_gt_f32_e64 s[62:63], s92, v39
	v_fmac_f32_e32 v55, v50, v9
	v_fmac_f32_e32 v55, v51, v7
	v_cndmask_b32_e64 v40, 0, 32, s[62:63]
	v_ldexp_f32 v39, v39, v40
	v_fmac_f32_e32 v55, v52, v5
	v_log_f32_e32 v39, v39
	v_fmac_f32_e32 v55, v53, v3
	v_mul_f32_e64 v41, |v55|, s90
	v_exp_f32_e32 v41, v41
	v_mul_f32_e32 v40, 0x3f317217, v39
	v_fma_f32 v40, v39, s41, -v40
	v_fmac_f32_e32 v40, 0x3377d1cf, v39
	v_fmac_f32_e32 v40, 0x3f317217, v39
	v_cmp_lt_f32_e64 s[64:65], |v39|, s68
	v_add_f32_e32 v41, 1.0, v41
	v_min_f32_e32 v38, 0, v54
	v_cndmask_b32_e64 v39, v39, v40, s[64:65]
	v_cndmask_b32_e64 v40, 0, v187, s[62:63]
	v_cmp_gt_f32_e64 s[62:63], s92, v41
	v_sub_f32_e32 v40, v39, v40
	v_min_f32_e32 v39, 0, v55
	v_cndmask_b32_e64 v42, 0, 32, s[62:63]
	v_ldexp_f32 v41, v41, v42
	v_log_f32_e32 v41, v41
	s_nop 0
	v_mul_f32_e32 v42, 0x3f317217, v41
	v_fma_f32 v42, v41, s41, -v42
	v_fmac_f32_e32 v42, 0x3377d1cf, v41
	v_fmac_f32_e32 v42, 0x3f317217, v41
	v_cmp_lt_f32_e64 s[64:65], |v41|, s68
	s_nop 1
	v_cndmask_b32_e64 v41, v41, v42, s[64:65]
	v_cndmask_b32_e64 v42, 0, v187, s[62:63]
	v_sub_f32_e32 v41, v41, v42
	v_sub_u32_e32 v42, 63, v124
	v_cndmask_b32_e32 v42, v42, v124, vcc
	v_lshl_add_u32 v54, v42, 7, s10
	ds_read_b128 v[42:45], v54
	ds_read_b128 v[46:49], v54 offset:16
	ds_read_b128 v[50:53], v54 offset:32
	ds_read_b128 v[54:57], v54 offset:48
	s_waitcnt lgkmcnt(3)
	v_fma_f32 v58, v42, v30, v0
	v_fmac_f32_e32 v58, v43, v32
	v_fmac_f32_e32 v58, v44, v26
	v_fmac_f32_e32 v58, v45, v28
	s_waitcnt lgkmcnt(2)
	v_fmac_f32_e32 v58, v46, v22
	v_fmac_f32_e32 v58, v47, v24
	v_fmac_f32_e32 v58, v48, v18
	v_fmac_f32_e32 v58, v49, v20
	s_waitcnt lgkmcnt(1)
	v_fmac_f32_e32 v58, v50, v16
	v_fmac_f32_e32 v58, v51, v14
	v_fmac_f32_e32 v58, v52, v10
	v_fmac_f32_e32 v58, v53, v12
	s_waitcnt lgkmcnt(0)
	v_fmac_f32_e32 v58, v54, v8
	v_fmac_f32_e32 v58, v55, v6
	v_fmac_f32_e32 v58, v56, v4
	v_fma_f32 v42, v42, v31, v1
	v_fmac_f32_e32 v58, v57, v2
	v_fmac_f32_e32 v42, v43, v33
	v_mul_f32_e64 v43, |v58|, s90
	v_exp_f32_e32 v43, v43
	v_fmac_f32_e32 v42, v44, v27
	v_fmac_f32_e32 v42, v45, v29
	v_fmac_f32_e32 v42, v46, v23
	v_add_f32_e32 v43, 1.0, v43
	v_cmp_gt_f32_e64 s[62:63], s92, v43
	v_fmac_f32_e32 v42, v47, v25
	v_fmac_f32_e32 v42, v48, v19
	v_cndmask_b32_e64 v45, 0, 32, s[62:63]
	v_ldexp_f32 v43, v43, v45
	v_fmac_f32_e32 v42, v49, v21
	v_log_f32_e32 v43, v43
	v_fmac_f32_e32 v42, v50, v17
	v_fmac_f32_e32 v42, v51, v15
	v_fmac_f32_e32 v42, v52, v11
	v_fmac_f32_e32 v42, v53, v13
	v_mul_f32_e32 v45, 0x3f317217, v43
	v_fmac_f32_e32 v42, v54, v9
	v_fma_f32 v45, v43, s41, -v45
	v_fmac_f32_e32 v42, v55, v7
	v_fmac_f32_e32 v45, 0x3377d1cf, v43
	v_fmac_f32_e32 v42, v56, v5
	v_fmac_f32_e32 v45, 0x3f317217, v43
	v_cmp_lt_f32_e64 s[64:65], |v43|, s68
	v_fmac_f32_e32 v42, v57, v3
	v_min_f32_e32 v44, 0, v58
	v_cndmask_b32_e64 v43, v43, v45, s[64:65]
	v_cndmask_b32_e64 v45, 0, v187, s[62:63]
	v_sub_f32_e32 v46, v43, v45
	v_min_f32_e32 v45, 0, v42
	v_mul_f32_e64 v42, |v42|, s90
	v_exp_f32_e32 v42, v42
	s_nop 0
	v_add_f32_e32 v42, 1.0, v42
	v_cmp_gt_f32_e64 s[62:63], s92, v42
	s_nop 1
	v_cndmask_b32_e64 v43, 0, 32, s[62:63]
	v_ldexp_f32 v42, v42, v43
	v_log_f32_e32 v42, v42
	s_nop 0
	v_mul_f32_e32 v43, 0x3f317217, v42
	v_fma_f32 v43, v42, s41, -v43
	v_fmac_f32_e32 v43, 0x3377d1cf, v42
	v_fmac_f32_e32 v43, 0x3f317217, v42
	v_cmp_lt_f32_e64 s[64:65], |v42|, s68
	s_nop 1
	v_cndmask_b32_e64 v42, v42, v43, s[64:65]
	v_cndmask_b32_e64 v43, 0, v187, s[62:63]
	v_sub_f32_e32 v47, v42, v43
	v_sub_u32_e32 v42, 63, v120
	v_cndmask_b32_e32 v42, v42, v120, vcc
	v_lshl_add_u32 v42, v42, 7, s10
	ds_read_b128 v[48:51], v42
	ds_read_b128 v[52:55], v42 offset:16
	ds_read_b128 v[56:59], v42 offset:32
	ds_read_b128 v[60:63], v42 offset:48
	s_waitcnt lgkmcnt(3)
	v_fma_f32 v42, v48, v30, v0
	v_fmac_f32_e32 v42, v49, v32
	v_fmac_f32_e32 v42, v50, v26
	v_fmac_f32_e32 v42, v51, v28
	s_waitcnt lgkmcnt(2)
	v_fmac_f32_e32 v42, v52, v22
	v_fmac_f32_e32 v42, v53, v24
	v_fmac_f32_e32 v42, v54, v18
	v_fmac_f32_e32 v42, v55, v20
	s_waitcnt lgkmcnt(1)
	v_fmac_f32_e32 v42, v56, v16
	v_fmac_f32_e32 v42, v57, v14
	v_fmac_f32_e32 v42, v58, v10
	v_fmac_f32_e32 v42, v59, v12
	s_waitcnt lgkmcnt(0)
	v_fmac_f32_e32 v42, v60, v8
	v_fmac_f32_e32 v42, v61, v6
	v_fmac_f32_e32 v42, v62, v4
	v_fmac_f32_e32 v42, v63, v2
	v_fma_f32 v43, v48, v31, v1
	v_min_f32_e32 v48, 0, v42
	v_mul_f32_e64 v42, |v42|, s90
	v_exp_f32_e32 v42, v42
	v_fmac_f32_e32 v43, v49, v33
	v_fmac_f32_e32 v43, v50, v27
	v_fmac_f32_e32 v43, v51, v29
	v_add_f32_e32 v42, 1.0, v42
	v_fmac_f32_e32 v43, v52, v23
	v_cmp_gt_f32_e64 s[62:63], s92, v42
	v_fmac_f32_e32 v43, v53, v25
	v_fmac_f32_e32 v43, v54, v19
	v_cndmask_b32_e64 v49, 0, 32, s[62:63]
	v_ldexp_f32 v42, v42, v49
	v_fmac_f32_e32 v43, v55, v21
	v_log_f32_e32 v42, v42
	v_fmac_f32_e32 v43, v56, v17
	v_fmac_f32_e32 v43, v57, v15
	v_fmac_f32_e32 v43, v58, v11
	v_fmac_f32_e32 v43, v59, v13
	v_mul_f32_e32 v49, 0x3f317217, v42
	v_fmac_f32_e32 v43, v60, v9
	v_fma_f32 v49, v42, s41, -v49
	v_fmac_f32_e32 v43, v61, v7
	v_fmac_f32_e32 v49, 0x3377d1cf, v42
	v_fmac_f32_e32 v43, v62, v5
	v_fmac_f32_e32 v49, 0x3f317217, v42
	v_cmp_lt_f32_e64 s[64:65], |v42|, s68
	v_fmac_f32_e32 v43, v63, v3
	s_nop 0
	v_cndmask_b32_e64 v42, v42, v49, s[64:65]
	v_cndmask_b32_e64 v49, 0, v187, s[62:63]
	v_sub_f32_e32 v50, v42, v49
	v_mul_f32_e64 v42, |v43|, s90
	v_exp_f32_e32 v42, v42
	v_min_f32_e32 v49, 0, v43
	v_add_f32_e32 v42, 1.0, v42
	v_cmp_gt_f32_e64 s[62:63], s92, v42
	s_nop 1
	v_cndmask_b32_e64 v43, 0, 32, s[62:63]
	v_ldexp_f32 v42, v42, v43
	v_log_f32_e32 v42, v42
	s_nop 0
	v_mul_f32_e32 v43, 0x3f317217, v42
	v_fma_f32 v43, v42, s41, -v43
	v_fmac_f32_e32 v43, 0x3377d1cf, v42
	v_fmac_f32_e32 v43, 0x3f317217, v42
	v_cmp_lt_f32_e64 s[64:65], |v42|, s68
	s_nop 1
	v_cndmask_b32_e64 v42, v42, v43, s[64:65]
	v_cndmask_b32_e64 v43, 0, v187, s[62:63]
	v_sub_f32_e32 v51, v42, v43
	v_sub_u32_e32 v42, 63, v117
	v_cndmask_b32_e32 v42, v42, v117, vcc
	v_lshl_add_u32 v42, v42, 7, s10
	ds_read_b128 v[52:55], v42
	ds_read_b128 v[56:59], v42 offset:16
	ds_read_b128 v[60:63], v42 offset:32
	ds_read_b128 v[66:69], v42 offset:48
	s_waitcnt lgkmcnt(3)
	v_fma_f32 v42, v52, v30, v0
	v_fmac_f32_e32 v42, v53, v32
	v_fmac_f32_e32 v42, v54, v26
	v_fmac_f32_e32 v42, v55, v28
	s_waitcnt lgkmcnt(2)
	v_fmac_f32_e32 v42, v56, v22
	v_fmac_f32_e32 v42, v57, v24
	v_fmac_f32_e32 v42, v58, v18
	v_fmac_f32_e32 v42, v59, v20
	s_waitcnt lgkmcnt(1)
	v_fmac_f32_e32 v42, v60, v16
	v_fmac_f32_e32 v42, v61, v14
	v_fmac_f32_e32 v42, v62, v10
	v_fmac_f32_e32 v42, v63, v12
	s_waitcnt lgkmcnt(0)
	v_fmac_f32_e32 v42, v66, v8
	v_fmac_f32_e32 v42, v67, v6
	v_fmac_f32_e32 v42, v68, v4
	v_fmac_f32_e32 v42, v69, v2
	v_fma_f32 v43, v52, v31, v1
	v_min_f32_e32 v52, 0, v42
	v_mul_f32_e64 v42, |v42|, s90
	v_exp_f32_e32 v42, v42
	v_fmac_f32_e32 v43, v53, v33
	v_fmac_f32_e32 v43, v54, v27
	v_fmac_f32_e32 v43, v55, v29
	v_add_f32_e32 v42, 1.0, v42
	v_fmac_f32_e32 v43, v56, v23
	v_cmp_gt_f32_e64 s[62:63], s92, v42
	v_fmac_f32_e32 v43, v57, v25
	v_fmac_f32_e32 v43, v58, v19
	v_cndmask_b32_e64 v53, 0, 32, s[62:63]
	v_ldexp_f32 v42, v42, v53
	v_fmac_f32_e32 v43, v59, v21
	v_log_f32_e32 v42, v42
	v_fmac_f32_e32 v43, v60, v17
	v_fmac_f32_e32 v43, v61, v15
	v_fmac_f32_e32 v43, v62, v11
	v_fmac_f32_e32 v43, v63, v13
	v_mul_f32_e32 v53, 0x3f317217, v42
	v_fmac_f32_e32 v43, v66, v9
	v_fma_f32 v53, v42, s41, -v53
	v_fmac_f32_e32 v43, v67, v7
	v_fmac_f32_e32 v53, 0x3377d1cf, v42
	v_fmac_f32_e32 v43, v68, v5
	v_fmac_f32_e32 v53, 0x3f317217, v42
	v_cmp_lt_f32_e64 s[64:65], |v42|, s68
	v_fmac_f32_e32 v43, v69, v3
	s_nop 0
	v_cndmask_b32_e64 v42, v42, v53, s[64:65]
	v_cndmask_b32_e64 v53, 0, v187, s[62:63]
	v_sub_f32_e32 v54, v42, v53
	v_mul_f32_e64 v42, |v43|, s90
	v_exp_f32_e32 v42, v42
	v_min_f32_e32 v53, 0, v43
	v_add_f32_e32 v42, 1.0, v42
	v_cmp_gt_f32_e64 s[62:63], s92, v42
	s_nop 1
	v_cndmask_b32_e64 v43, 0, 32, s[62:63]
	v_ldexp_f32 v42, v42, v43
	v_log_f32_e32 v42, v42
	s_nop 0
	v_mul_f32_e32 v43, 0x3f317217, v42
	v_fma_f32 v43, v42, s41, -v43
	v_fmac_f32_e32 v43, 0x3377d1cf, v42
	v_fmac_f32_e32 v43, 0x3f317217, v42
	v_cmp_lt_f32_e64 s[64:65], |v42|, s68
	s_nop 1
	v_cndmask_b32_e64 v42, v42, v43, s[64:65]
	v_cndmask_b32_e64 v43, 0, v187, s[62:63]
	v_sub_f32_e32 v55, v42, v43
	v_pk_fma_f32 v[42:43], v[34:35], s[2:3], 0 op_sel_hi:[1,0,0]
	v_pk_add_f32 v[34:35], v[38:39], v[40:41] neg_lo:[0,1] neg_hi:[0,1]
	s_nop 0
	v_pk_fma_f32 v[40:41], v[34:35], s[2:3], v[42:43] op_sel_hi:[1,0,1]
	v_pk_add_f32 v[34:35], v[44:45], v[46:47] neg_lo:[0,1] neg_hi:[0,1]
	v_sub_u32_e32 v44, 63, v114
	v_cndmask_b32_e32 v44, v44, v114, vcc
	v_pk_fma_f32 v[38:39], v[34:35], s[2:3], v[40:41] op_sel_hi:[1,0,1]
	v_pk_add_f32 v[34:35], v[48:49], v[50:51] neg_lo:[0,1] neg_hi:[0,1]
	v_lshl_add_u32 v56, v44, 7, s10
	v_pk_fma_f32 v[36:37], v[34:35], s[2:3], v[38:39] op_sel_hi:[1,0,1]
	v_pk_add_f32 v[34:35], v[52:53], v[54:55] neg_lo:[0,1] neg_hi:[0,1]
	ds_read_b128 v[44:47], v56
	ds_read_b128 v[48:51], v56 offset:16
	ds_read_b128 v[52:55], v56 offset:32
	ds_read_b128 v[56:59], v56 offset:48
	v_pk_fma_f32 v[34:35], v[34:35], s[2:3], v[36:37] op_sel_hi:[1,0,1]
	s_waitcnt lgkmcnt(3)
	v_fma_f32 v60, v44, v30, v0
	v_fmac_f32_e32 v60, v45, v32
	v_fmac_f32_e32 v60, v46, v26
	v_fmac_f32_e32 v60, v47, v28
	s_waitcnt lgkmcnt(2)
	v_fmac_f32_e32 v60, v48, v22
	v_fmac_f32_e32 v60, v49, v24
	v_fmac_f32_e32 v60, v50, v18
	v_fmac_f32_e32 v60, v51, v20
	s_waitcnt lgkmcnt(1)
	v_fmac_f32_e32 v60, v52, v16
	v_fmac_f32_e32 v60, v53, v14
	v_fmac_f32_e32 v60, v54, v10
	v_fma_f32 v61, v44, v31, v1
	v_fmac_f32_e32 v60, v55, v12
	v_fmac_f32_e32 v61, v45, v33
	s_waitcnt lgkmcnt(0)
	v_fmac_f32_e32 v60, v56, v8
	v_fmac_f32_e32 v61, v46, v27
	v_fmac_f32_e32 v60, v57, v6
	v_fmac_f32_e32 v61, v47, v29
	v_fmac_f32_e32 v60, v58, v4
	v_fmac_f32_e32 v61, v48, v23
	v_fmac_f32_e32 v60, v59, v2
	v_fmac_f32_e32 v61, v49, v25
	v_mul_f32_e64 v45, |v60|, s90
	v_fmac_f32_e32 v61, v50, v19
	v_exp_f32_e32 v45, v45
	v_fmac_f32_e32 v61, v51, v21
	v_fmac_f32_e32 v61, v52, v17
	v_fmac_f32_e32 v61, v53, v15
	v_fmac_f32_e32 v61, v54, v11
	v_add_f32_e32 v45, 1.0, v45
	v_fmac_f32_e32 v61, v55, v13
	v_cmp_gt_f32_e64 s[62:63], s92, v45
	v_fmac_f32_e32 v61, v56, v9
	v_fmac_f32_e32 v61, v57, v7
	v_cndmask_b32_e64 v46, 0, 32, s[62:63]
	v_ldexp_f32 v45, v45, v46
	v_fmac_f32_e32 v61, v58, v5
	v_log_f32_e32 v45, v45
	v_fmac_f32_e32 v61, v59, v3
	v_mul_f32_e64 v47, |v61|, s90
	v_exp_f32_e32 v47, v47
	v_mul_f32_e32 v46, 0x3f317217, v45
	v_fma_f32 v46, v45, s41, -v46
	v_fmac_f32_e32 v46, 0x3377d1cf, v45
	v_fmac_f32_e32 v46, 0x3f317217, v45
	v_cmp_lt_f32_e64 s[64:65], |v45|, s68
	v_add_f32_e32 v47, 1.0, v47
	v_min_f32_e32 v44, 0, v60
	v_cndmask_b32_e64 v45, v45, v46, s[64:65]
	v_cndmask_b32_e64 v46, 0, v187, s[62:63]
	v_cmp_gt_f32_e64 s[62:63], s92, v47
	v_sub_f32_e32 v46, v45, v46
	v_min_f32_e32 v45, 0, v61
	v_cndmask_b32_e64 v48, 0, 32, s[62:63]
	v_ldexp_f32 v47, v47, v48
	v_log_f32_e32 v47, v47
	s_nop 0
	v_mul_f32_e32 v48, 0x3f317217, v47
	v_fma_f32 v48, v47, s41, -v48
	v_fmac_f32_e32 v48, 0x3377d1cf, v47
	v_fmac_f32_e32 v48, 0x3f317217, v47
	v_cmp_lt_f32_e64 s[64:65], |v47|, s68
	s_nop 1
	v_cndmask_b32_e64 v47, v47, v48, s[64:65]
	v_cndmask_b32_e64 v48, 0, v187, s[62:63]
	v_sub_f32_e32 v47, v47, v48
	v_pk_add_f32 v[44:45], v[44:45], v[46:47] neg_lo:[0,1] neg_hi:[0,1]
	v_sub_u32_e32 v46, 63, v111
	v_cndmask_b32_e32 v46, v46, v111, vcc
	v_lshl_add_u32 v58, v46, 7, s10
	ds_read_b128 v[46:49], v58
	ds_read_b128 v[50:53], v58 offset:16
	ds_read_b128 v[54:57], v58 offset:32
	ds_read_b128 v[58:61], v58 offset:48
	s_waitcnt lgkmcnt(3)
	v_fma_f32 v62, v46, v30, v0
	v_fmac_f32_e32 v62, v47, v32
	v_fmac_f32_e32 v62, v48, v26
	v_fmac_f32_e32 v62, v49, v28
	s_waitcnt lgkmcnt(2)
	v_fmac_f32_e32 v62, v50, v22
	v_fmac_f32_e32 v62, v51, v24
	v_fmac_f32_e32 v62, v52, v18
	v_fmac_f32_e32 v62, v53, v20
	s_waitcnt lgkmcnt(1)
	v_fmac_f32_e32 v62, v54, v16
	v_fmac_f32_e32 v62, v55, v14
	v_fmac_f32_e32 v62, v56, v10
	v_fma_f32 v63, v46, v31, v1
	v_fmac_f32_e32 v62, v57, v12
	v_fmac_f32_e32 v63, v47, v33
	s_waitcnt lgkmcnt(0)
	v_fmac_f32_e32 v62, v58, v8
	v_fmac_f32_e32 v63, v48, v27
	v_fmac_f32_e32 v62, v59, v6
	v_fmac_f32_e32 v63, v49, v29
	v_fmac_f32_e32 v62, v60, v4
	v_fmac_f32_e32 v63, v50, v23
	v_fmac_f32_e32 v62, v61, v2
	v_fmac_f32_e32 v63, v51, v25
	v_mul_f32_e64 v47, |v62|, s90
	v_fmac_f32_e32 v63, v52, v19
	v_exp_f32_e32 v47, v47
	v_fmac_f32_e32 v63, v53, v21
	v_fmac_f32_e32 v63, v54, v17
	v_fmac_f32_e32 v63, v55, v15
	v_fmac_f32_e32 v63, v56, v11
	v_add_f32_e32 v47, 1.0, v47
	v_fmac_f32_e32 v63, v57, v13
	v_cmp_gt_f32_e64 s[62:63], s92, v47
	v_fmac_f32_e32 v63, v58, v9
	v_fmac_f32_e32 v63, v59, v7
	v_cndmask_b32_e64 v48, 0, 32, s[62:63]
	v_ldexp_f32 v47, v47, v48
	v_fmac_f32_e32 v63, v60, v5
	v_log_f32_e32 v47, v47
	v_fmac_f32_e32 v63, v61, v3
	v_mul_f32_e64 v49, |v63|, s90
	v_exp_f32_e32 v49, v49
	v_mul_f32_e32 v48, 0x3f317217, v47
	v_fma_f32 v48, v47, s41, -v48
	v_fmac_f32_e32 v48, 0x3377d1cf, v47
	v_fmac_f32_e32 v48, 0x3f317217, v47
	v_cmp_lt_f32_e64 s[64:65], |v47|, s68
	v_add_f32_e32 v49, 1.0, v49
	v_min_f32_e32 v46, 0, v62
	v_cndmask_b32_e64 v47, v47, v48, s[64:65]
	v_cndmask_b32_e64 v48, 0, v187, s[62:63]
	v_cmp_gt_f32_e64 s[62:63], s92, v49
	v_sub_f32_e32 v48, v47, v48
	v_min_f32_e32 v47, 0, v63
	v_cndmask_b32_e64 v50, 0, 32, s[62:63]
	v_ldexp_f32 v49, v49, v50
	v_log_f32_e32 v49, v49
	s_nop 0
	v_mul_f32_e32 v50, 0x3f317217, v49
	v_fma_f32 v50, v49, s41, -v50
	v_fmac_f32_e32 v50, 0x3377d1cf, v49
	v_fmac_f32_e32 v50, 0x3f317217, v49
	v_cmp_lt_f32_e64 s[64:65], |v49|, s68
	s_nop 1
	v_cndmask_b32_e64 v49, v49, v50, s[64:65]
	v_cndmask_b32_e64 v50, 0, v187, s[62:63]
	v_sub_f32_e32 v49, v49, v50
	v_pk_add_f32 v[46:47], v[46:47], v[48:49] neg_lo:[0,1] neg_hi:[0,1]
	v_sub_u32_e32 v48, 63, v108
	v_cndmask_b32_e32 v48, v48, v108, vcc
	v_lshl_add_u32 v60, v48, 7, s10
	ds_read_b128 v[48:51], v60
	ds_read_b128 v[52:55], v60 offset:16
	ds_read_b128 v[56:59], v60 offset:32
	ds_read_b128 v[60:63], v60 offset:48
	s_waitcnt lgkmcnt(3)
	v_fma_f32 v66, v48, v30, v0
	v_fmac_f32_e32 v66, v49, v32
	v_fmac_f32_e32 v66, v50, v26
	v_fmac_f32_e32 v66, v51, v28
	s_waitcnt lgkmcnt(2)
	v_fmac_f32_e32 v66, v52, v22
	v_fmac_f32_e32 v66, v53, v24
	v_fmac_f32_e32 v66, v54, v18
	v_fmac_f32_e32 v66, v55, v20
	s_waitcnt lgkmcnt(1)
	v_fmac_f32_e32 v66, v56, v16
	v_fmac_f32_e32 v66, v57, v14
	v_fmac_f32_e32 v66, v58, v10
	v_fma_f32 v67, v48, v31, v1
	v_fmac_f32_e32 v66, v59, v12
	v_fmac_f32_e32 v67, v49, v33
	s_waitcnt lgkmcnt(0)
	v_fmac_f32_e32 v66, v60, v8
	v_fmac_f32_e32 v67, v50, v27
	v_fmac_f32_e32 v66, v61, v6
	v_fmac_f32_e32 v67, v51, v29
	v_fmac_f32_e32 v66, v62, v4
	v_fmac_f32_e32 v67, v52, v23
	v_fmac_f32_e32 v66, v63, v2
	v_fmac_f32_e32 v67, v53, v25
	v_mul_f32_e64 v49, |v66|, s90
	v_fmac_f32_e32 v67, v54, v19
	v_exp_f32_e32 v49, v49
	v_fmac_f32_e32 v67, v55, v21
	v_fmac_f32_e32 v67, v56, v17
	v_fmac_f32_e32 v67, v57, v15
	v_fmac_f32_e32 v67, v58, v11
	v_add_f32_e32 v49, 1.0, v49
	v_fmac_f32_e32 v67, v59, v13
	v_cmp_gt_f32_e64 s[62:63], s92, v49
	v_fmac_f32_e32 v67, v60, v9
	v_fmac_f32_e32 v67, v61, v7
	v_cndmask_b32_e64 v50, 0, 32, s[62:63]
	v_ldexp_f32 v49, v49, v50
	v_fmac_f32_e32 v67, v62, v5
	v_log_f32_e32 v49, v49
	v_fmac_f32_e32 v67, v63, v3
	v_mul_f32_e64 v51, |v67|, s90
	v_exp_f32_e32 v51, v51
	v_mul_f32_e32 v50, 0x3f317217, v49
	v_fma_f32 v50, v49, s41, -v50
	v_fmac_f32_e32 v50, 0x3377d1cf, v49
	v_fmac_f32_e32 v50, 0x3f317217, v49
	v_cmp_lt_f32_e64 s[64:65], |v49|, s68
	v_add_f32_e32 v51, 1.0, v51
	v_min_f32_e32 v48, 0, v66
	v_cndmask_b32_e64 v49, v49, v50, s[64:65]
	v_cndmask_b32_e64 v50, 0, v187, s[62:63]
	v_cmp_gt_f32_e64 s[62:63], s92, v51
	v_sub_f32_e32 v50, v49, v50
	v_min_f32_e32 v49, 0, v67
	v_cndmask_b32_e64 v52, 0, 32, s[62:63]
	v_ldexp_f32 v51, v51, v52
	v_log_f32_e32 v51, v51
	s_nop 0
	v_mul_f32_e32 v52, 0x3f317217, v51
	v_fma_f32 v52, v51, s41, -v52
	v_fmac_f32_e32 v52, 0x3377d1cf, v51
	v_fmac_f32_e32 v52, 0x3f317217, v51
	v_cmp_lt_f32_e64 s[64:65], |v51|, s68
	s_nop 1
	v_cndmask_b32_e64 v51, v51, v52, s[64:65]
	v_cndmask_b32_e64 v52, 0, v187, s[62:63]
	v_sub_f32_e32 v51, v51, v52
	v_sub_u32_e32 v52, 63, v105
	v_cndmask_b32_e32 v52, v52, v105, vcc
	v_lshl_add_u32 v66, v52, 7, s10
	ds_read_b128 v[52:55], v66
	ds_read_b128 v[56:59], v66 offset:16
	ds_read_b128 v[60:63], v66 offset:32
	ds_read_b128 v[66:69], v66 offset:48
	s_waitcnt lgkmcnt(3)
	v_fma_f32 v70, v52, v30, v0
	v_fmac_f32_e32 v70, v53, v32
	v_fmac_f32_e32 v70, v54, v26
	v_fmac_f32_e32 v70, v55, v28
	s_waitcnt lgkmcnt(2)
	v_fmac_f32_e32 v70, v56, v22
	v_fmac_f32_e32 v70, v57, v24
	v_fmac_f32_e32 v70, v58, v18
	v_fmac_f32_e32 v70, v59, v20
	s_waitcnt lgkmcnt(1)
	v_fmac_f32_e32 v70, v60, v16
	v_fmac_f32_e32 v70, v61, v14
	v_fmac_f32_e32 v70, v62, v10
	v_fma_f32 v71, v52, v31, v1
	v_fmac_f32_e32 v70, v63, v12
	v_fmac_f32_e32 v71, v53, v33
	s_waitcnt lgkmcnt(0)
	v_fmac_f32_e32 v70, v66, v8
	v_fmac_f32_e32 v71, v54, v27
	v_fmac_f32_e32 v70, v67, v6
	v_fmac_f32_e32 v71, v55, v29
	v_fmac_f32_e32 v70, v68, v4
	v_fmac_f32_e32 v71, v56, v23
	v_fmac_f32_e32 v70, v69, v2
	v_fmac_f32_e32 v71, v57, v25
	v_mul_f32_e64 v53, |v70|, s90
	v_fmac_f32_e32 v71, v58, v19
	v_exp_f32_e32 v53, v53
	v_fmac_f32_e32 v71, v59, v21
	v_fmac_f32_e32 v71, v60, v17
	v_fmac_f32_e32 v71, v61, v15
	v_fmac_f32_e32 v71, v62, v11
	v_add_f32_e32 v53, 1.0, v53
	v_fmac_f32_e32 v71, v63, v13
	v_cmp_gt_f32_e64 s[62:63], s92, v53
	v_fmac_f32_e32 v71, v66, v9
	v_fmac_f32_e32 v71, v67, v7
	v_cndmask_b32_e64 v54, 0, 32, s[62:63]
	v_ldexp_f32 v53, v53, v54
	v_fmac_f32_e32 v71, v68, v5
	v_log_f32_e32 v53, v53
	v_fmac_f32_e32 v71, v69, v3
	v_mul_f32_e64 v55, |v71|, s90
	v_exp_f32_e32 v55, v55
	v_mul_f32_e32 v54, 0x3f317217, v53
	v_fma_f32 v54, v53, s41, -v54
	v_fmac_f32_e32 v54, 0x3377d1cf, v53
	v_fmac_f32_e32 v54, 0x3f317217, v53
	v_cmp_lt_f32_e64 s[64:65], |v53|, s68
	v_add_f32_e32 v55, 1.0, v55
	v_min_f32_e32 v52, 0, v70
	v_cndmask_b32_e64 v53, v53, v54, s[64:65]
	v_cndmask_b32_e64 v54, 0, v187, s[62:63]
	v_cmp_gt_f32_e64 s[62:63], s92, v55
	v_sub_f32_e32 v54, v53, v54
	v_min_f32_e32 v53, 0, v71
	v_cndmask_b32_e64 v56, 0, 32, s[62:63]
	v_ldexp_f32 v55, v55, v56
	v_log_f32_e32 v55, v55
	s_nop 0
	v_mul_f32_e32 v56, 0x3f317217, v55
	v_fma_f32 v56, v55, s41, -v56
	v_fmac_f32_e32 v56, 0x3377d1cf, v55
	v_fmac_f32_e32 v56, 0x3f317217, v55
	v_cmp_lt_f32_e64 s[64:65], |v55|, s68
	s_nop 1
	v_cndmask_b32_e64 v55, v55, v56, s[64:65]
	v_cndmask_b32_e64 v56, 0, v187, s[62:63]
	v_sub_f32_e32 v55, v55, v56
	v_sub_u32_e32 v56, 63, v101
	v_cndmask_b32_e32 v56, v56, v101, vcc
	v_lshl_add_u32 v70, v56, 7, s10
	ds_read_b128 v[56:59], v70
	ds_read_b128 v[60:63], v70 offset:16
	ds_read_b128 v[66:69], v70 offset:32
	ds_read_b128 v[70:73], v70 offset:48
	s_waitcnt lgkmcnt(3)
	v_fma_f32 v74, v56, v30, v0
	v_fmac_f32_e32 v74, v57, v32
	v_fmac_f32_e32 v74, v58, v26
	v_fmac_f32_e32 v74, v59, v28
	s_waitcnt lgkmcnt(2)
	v_fmac_f32_e32 v74, v60, v22
	v_fmac_f32_e32 v74, v61, v24
	v_fmac_f32_e32 v74, v62, v18
	v_fmac_f32_e32 v74, v63, v20
	s_waitcnt lgkmcnt(1)
	v_fmac_f32_e32 v74, v66, v16
	v_fmac_f32_e32 v74, v67, v14
	v_fmac_f32_e32 v74, v68, v10
	v_fma_f32 v75, v56, v31, v1
	v_fmac_f32_e32 v74, v69, v12
	v_fmac_f32_e32 v75, v57, v33
	s_waitcnt lgkmcnt(0)
	v_fmac_f32_e32 v74, v70, v8
	v_fmac_f32_e32 v75, v58, v27
	v_fmac_f32_e32 v74, v71, v6
	v_fmac_f32_e32 v75, v59, v29
	v_fmac_f32_e32 v74, v72, v4
	v_fmac_f32_e32 v75, v60, v23
	v_fmac_f32_e32 v74, v73, v2
	v_fmac_f32_e32 v75, v61, v25
	v_mul_f32_e64 v57, |v74|, s90
	v_fmac_f32_e32 v75, v62, v19
	v_exp_f32_e32 v57, v57
	v_fmac_f32_e32 v75, v63, v21
	v_fmac_f32_e32 v75, v66, v17
	v_fmac_f32_e32 v75, v67, v15
	v_fmac_f32_e32 v75, v68, v11
	v_add_f32_e32 v57, 1.0, v57
	v_fmac_f32_e32 v75, v69, v13
	v_cmp_gt_f32_e64 s[62:63], s92, v57
	v_fmac_f32_e32 v75, v70, v9
	v_fmac_f32_e32 v75, v71, v7
	v_cndmask_b32_e64 v58, 0, 32, s[62:63]
	v_ldexp_f32 v57, v57, v58
	v_fmac_f32_e32 v75, v72, v5
	v_log_f32_e32 v57, v57
	v_fmac_f32_e32 v75, v73, v3
	v_mul_f32_e64 v59, |v75|, s90
	v_exp_f32_e32 v59, v59
	v_mul_f32_e32 v58, 0x3f317217, v57
	v_fma_f32 v58, v57, s41, -v58
	v_fmac_f32_e32 v58, 0x3377d1cf, v57
	v_fmac_f32_e32 v58, 0x3f317217, v57
	v_cmp_lt_f32_e64 s[64:65], |v57|, s68
	v_add_f32_e32 v59, 1.0, v59
	v_min_f32_e32 v56, 0, v74
	v_cndmask_b32_e64 v57, v57, v58, s[64:65]
	v_cndmask_b32_e64 v58, 0, v187, s[62:63]
	v_cmp_gt_f32_e64 s[62:63], s92, v59
	v_sub_f32_e32 v58, v57, v58
	v_min_f32_e32 v57, 0, v75
	v_cndmask_b32_e64 v60, 0, 32, s[62:63]
	v_ldexp_f32 v59, v59, v60
	v_log_f32_e32 v59, v59
	s_nop 0
	v_mul_f32_e32 v60, 0x3f317217, v59
	v_fma_f32 v60, v59, s41, -v60
	v_fmac_f32_e32 v60, 0x3377d1cf, v59
	v_fmac_f32_e32 v60, 0x3f317217, v59
	v_cmp_lt_f32_e64 s[64:65], |v59|, s68
	s_nop 1
	v_cndmask_b32_e64 v59, v59, v60, s[64:65]
	v_cndmask_b32_e64 v60, 0, v187, s[62:63]
	v_sub_f32_e32 v59, v59, v60
	v_sub_u32_e32 v60, 63, v98
	v_cndmask_b32_e32 v60, v60, v98, vcc
	v_lshl_add_u32 v74, v60, 7, s10
	ds_read_b128 v[60:63], v74
	ds_read_b128 v[66:69], v74 offset:16
	ds_read_b128 v[70:73], v74 offset:32
	ds_read_b128 v[74:77], v74 offset:48
	s_waitcnt lgkmcnt(3)
	v_fma_f32 v78, v60, v30, v0
	v_fmac_f32_e32 v78, v61, v32
	v_fmac_f32_e32 v78, v62, v26
	v_fmac_f32_e32 v78, v63, v28
	s_waitcnt lgkmcnt(2)
	v_fmac_f32_e32 v78, v66, v22
	v_fmac_f32_e32 v78, v67, v24
	v_fmac_f32_e32 v78, v68, v18
	v_fmac_f32_e32 v78, v69, v20
	s_waitcnt lgkmcnt(1)
	v_fmac_f32_e32 v78, v70, v16
	v_fmac_f32_e32 v78, v71, v14
	v_fmac_f32_e32 v78, v72, v10
	v_fma_f32 v79, v60, v31, v1
	v_fmac_f32_e32 v78, v73, v12
	v_fmac_f32_e32 v79, v61, v33
	s_waitcnt lgkmcnt(0)
	v_fmac_f32_e32 v78, v74, v8
	v_fmac_f32_e32 v79, v62, v27
	v_fmac_f32_e32 v78, v75, v6
	v_fmac_f32_e32 v79, v63, v29
	v_fmac_f32_e32 v78, v76, v4
	v_fmac_f32_e32 v79, v66, v23
	v_fmac_f32_e32 v78, v77, v2
	v_fmac_f32_e32 v79, v67, v25
	v_mul_f32_e64 v61, |v78|, s90
	v_fmac_f32_e32 v79, v68, v19
	v_exp_f32_e32 v61, v61
	v_fmac_f32_e32 v79, v69, v21
	v_fmac_f32_e32 v79, v70, v17
	v_fmac_f32_e32 v79, v71, v15
	v_fmac_f32_e32 v79, v72, v11
	v_add_f32_e32 v61, 1.0, v61
	v_fmac_f32_e32 v79, v73, v13
	v_cmp_gt_f32_e64 s[62:63], s92, v61
	v_fmac_f32_e32 v79, v74, v9
	v_fmac_f32_e32 v79, v75, v7
	v_cndmask_b32_e64 v62, 0, 32, s[62:63]
	v_ldexp_f32 v61, v61, v62
	v_fmac_f32_e32 v79, v76, v5
	v_log_f32_e32 v61, v61
	v_fmac_f32_e32 v79, v77, v3
	v_mul_f32_e64 v63, |v79|, s90
	v_exp_f32_e32 v63, v63
	v_mul_f32_e32 v62, 0x3f317217, v61
	v_fma_f32 v62, v61, s41, -v62
	v_fmac_f32_e32 v62, 0x3377d1cf, v61
	v_fmac_f32_e32 v62, 0x3f317217, v61
	v_cmp_lt_f32_e64 s[64:65], |v61|, s68
	v_add_f32_e32 v63, 1.0, v63
	v_min_f32_e32 v60, 0, v78
	v_cndmask_b32_e64 v61, v61, v62, s[64:65]
	v_cndmask_b32_e64 v62, 0, v187, s[62:63]
	v_cmp_gt_f32_e64 s[62:63], s92, v63
	v_sub_f32_e32 v62, v61, v62
	v_min_f32_e32 v61, 0, v79
	v_cndmask_b32_e64 v66, 0, 32, s[62:63]
	v_ldexp_f32 v63, v63, v66
	v_log_f32_e32 v63, v63
	s_nop 0
	v_mul_f32_e32 v66, 0x3f317217, v63
	v_fma_f32 v66, v63, s41, -v66
	v_fmac_f32_e32 v66, 0x3377d1cf, v63
	v_fmac_f32_e32 v66, 0x3f317217, v63
	v_cmp_lt_f32_e64 s[64:65], |v63|, s68
	s_nop 1
	v_cndmask_b32_e64 v63, v63, v66, s[64:65]
	v_cndmask_b32_e64 v66, 0, v187, s[62:63]
	v_sub_f32_e32 v63, v63, v66
	v_sub_u32_e32 v66, 63, v95
	v_cndmask_b32_e32 v66, v66, v95, vcc
	v_lshl_add_u32 v78, v66, 7, s10
	ds_read_b128 v[66:69], v78
	ds_read_b128 v[70:73], v78 offset:16
	ds_read_b128 v[74:77], v78 offset:32
	ds_read_b128 v[78:81], v78 offset:48
	s_waitcnt lgkmcnt(3)
	v_fma_f32 v133, v66, v30, v0
	v_fmac_f32_e32 v133, v67, v32
	v_fmac_f32_e32 v133, v68, v26
	v_fmac_f32_e32 v133, v69, v28
	s_waitcnt lgkmcnt(2)
	v_fmac_f32_e32 v133, v70, v22
	v_fmac_f32_e32 v133, v71, v24
	v_fmac_f32_e32 v133, v72, v18
	v_fmac_f32_e32 v133, v73, v20
	s_waitcnt lgkmcnt(1)
	v_fmac_f32_e32 v133, v74, v16
	v_fmac_f32_e32 v133, v75, v14
	v_fmac_f32_e32 v133, v76, v10
	v_fma_f32 v134, v66, v31, v1
	v_fmac_f32_e32 v133, v77, v12
	v_fmac_f32_e32 v134, v67, v33
	s_waitcnt lgkmcnt(0)
	v_fmac_f32_e32 v133, v78, v8
	v_fmac_f32_e32 v134, v68, v27
	v_fmac_f32_e32 v133, v79, v6
	v_fmac_f32_e32 v134, v69, v29
	v_fmac_f32_e32 v133, v80, v4
	v_fmac_f32_e32 v134, v70, v23
	v_fmac_f32_e32 v133, v81, v2
	v_fmac_f32_e32 v134, v71, v25
	v_mul_f32_e64 v67, |v133|, s90
	v_fmac_f32_e32 v134, v72, v19
	v_exp_f32_e32 v67, v67
	v_fmac_f32_e32 v134, v73, v21
	v_fmac_f32_e32 v134, v74, v17
	v_fmac_f32_e32 v134, v75, v15
	v_fmac_f32_e32 v134, v76, v11
	v_add_f32_e32 v67, 1.0, v67
	v_fmac_f32_e32 v134, v77, v13
	v_cmp_gt_f32_e64 s[62:63], s92, v67
	v_fmac_f32_e32 v134, v78, v9
	v_fmac_f32_e32 v134, v79, v7
	v_cndmask_b32_e64 v68, 0, 32, s[62:63]
	v_ldexp_f32 v67, v67, v68
	v_fmac_f32_e32 v134, v80, v5
	v_log_f32_e32 v67, v67
	v_fmac_f32_e32 v134, v81, v3
	v_mul_f32_e64 v69, |v134|, s90
	v_exp_f32_e32 v69, v69
	v_mul_f32_e32 v68, 0x3f317217, v67
	v_fma_f32 v68, v67, s41, -v68
	v_fmac_f32_e32 v68, 0x3377d1cf, v67
	v_fmac_f32_e32 v68, 0x3f317217, v67
	v_cmp_lt_f32_e64 s[64:65], |v67|, s68
	v_add_f32_e32 v69, 1.0, v69
	v_min_f32_e32 v66, 0, v133
	v_cndmask_b32_e64 v67, v67, v68, s[64:65]
	v_cndmask_b32_e64 v68, 0, v187, s[62:63]
	v_cmp_gt_f32_e64 s[62:63], s92, v69
	v_sub_f32_e32 v68, v67, v68
	v_min_f32_e32 v67, 0, v134
	v_cndmask_b32_e64 v70, 0, 32, s[62:63]
	v_ldexp_f32 v69, v69, v70
	v_log_f32_e32 v69, v69
	s_nop 0
	v_mul_f32_e32 v70, 0x3f317217, v69
	v_fma_f32 v70, v69, s41, -v70
	v_fmac_f32_e32 v70, 0x3377d1cf, v69
	v_fmac_f32_e32 v70, 0x3f317217, v69
	v_cmp_lt_f32_e64 s[64:65], |v69|, s68
	s_nop 1
	v_cndmask_b32_e64 v69, v69, v70, s[64:65]
	v_cndmask_b32_e64 v70, 0, v187, s[62:63]
	v_sub_f32_e32 v69, v69, v70
	v_sub_u32_e32 v70, 63, v92
	v_cndmask_b32_e32 v70, v70, v92, vcc
	v_lshl_add_u32 v133, v70, 7, s10
	ds_read_b128 v[70:73], v133
	ds_read_b128 v[74:77], v133 offset:16
	ds_read_b128 v[78:81], v133 offset:32
	ds_read_b128 v[134:137], v133 offset:48
	s_waitcnt lgkmcnt(3)
	v_fma_f32 v133, v70, v30, v0
	v_fmac_f32_e32 v133, v71, v32
	v_fmac_f32_e32 v133, v72, v26
	v_fmac_f32_e32 v133, v73, v28
	s_waitcnt lgkmcnt(2)
	v_fmac_f32_e32 v133, v74, v22
	v_fmac_f32_e32 v133, v75, v24
	v_fmac_f32_e32 v133, v76, v18
	v_fmac_f32_e32 v133, v77, v20
	s_waitcnt lgkmcnt(1)
	v_fmac_f32_e32 v133, v78, v16
	v_fmac_f32_e32 v133, v79, v14
	v_fmac_f32_e32 v133, v80, v10
	v_fma_f32 v138, v70, v31, v1
	v_fmac_f32_e32 v133, v81, v12
	v_fmac_f32_e32 v138, v71, v33
	s_waitcnt lgkmcnt(0)
	v_fmac_f32_e32 v133, v134, v8
	v_fmac_f32_e32 v138, v72, v27
	v_fmac_f32_e32 v133, v135, v6
	v_fmac_f32_e32 v138, v73, v29
	v_fmac_f32_e32 v133, v136, v4
	v_fmac_f32_e32 v138, v74, v23
	v_fmac_f32_e32 v133, v137, v2
	v_fmac_f32_e32 v138, v75, v25
	v_mul_f32_e64 v71, |v133|, s90
	v_fmac_f32_e32 v138, v76, v19
	v_exp_f32_e32 v71, v71
	v_fmac_f32_e32 v138, v77, v21
	v_fmac_f32_e32 v138, v78, v17
	v_fmac_f32_e32 v138, v79, v15
	v_fmac_f32_e32 v138, v80, v11
	v_add_f32_e32 v71, 1.0, v71
	v_fmac_f32_e32 v138, v81, v13
	v_cmp_gt_f32_e64 s[62:63], s92, v71
	v_fmac_f32_e32 v138, v134, v9
	v_fmac_f32_e32 v138, v135, v7
	v_cndmask_b32_e64 v72, 0, 32, s[62:63]
	v_ldexp_f32 v71, v71, v72
	v_fmac_f32_e32 v138, v136, v5
	v_log_f32_e32 v71, v71
	v_fmac_f32_e32 v138, v137, v3
	v_mul_f32_e64 v73, |v138|, s90
	v_exp_f32_e32 v73, v73
	v_mul_f32_e32 v72, 0x3f317217, v71
	v_fma_f32 v72, v71, s41, -v72
	v_fmac_f32_e32 v72, 0x3377d1cf, v71
	v_fmac_f32_e32 v72, 0x3f317217, v71
	v_cmp_lt_f32_e64 s[64:65], |v71|, s68
	v_add_f32_e32 v73, 1.0, v73
	v_min_f32_e32 v70, 0, v133
	v_cndmask_b32_e64 v71, v71, v72, s[64:65]
	v_cndmask_b32_e64 v72, 0, v187, s[62:63]
	v_cmp_gt_f32_e64 s[62:63], s92, v73
	v_sub_f32_e32 v72, v71, v72
	v_min_f32_e32 v71, 0, v138
	v_cndmask_b32_e64 v74, 0, 32, s[62:63]
	v_ldexp_f32 v73, v73, v74
	v_log_f32_e32 v73, v73
	s_nop 0
	v_mul_f32_e32 v74, 0x3f317217, v73
	v_fma_f32 v74, v73, s41, -v74
	v_fmac_f32_e32 v74, 0x3377d1cf, v73
	v_fmac_f32_e32 v74, 0x3f317217, v73
	v_cmp_lt_f32_e64 s[64:65], |v73|, s68
	s_nop 1
	v_cndmask_b32_e64 v73, v73, v74, s[64:65]
	v_cndmask_b32_e64 v74, 0, v187, s[62:63]
	v_sub_f32_e32 v73, v73, v74
	v_sub_u32_e32 v74, 63, v89
	v_cndmask_b32_e32 v74, v74, v89, vcc
	v_lshl_add_u32 v133, v74, 7, s10
	ds_read_b128 v[74:77], v133
	ds_read_b128 v[78:81], v133 offset:16
	ds_read_b128 v[134:137], v133 offset:32
	ds_read_b128 v[138:141], v133 offset:48
	s_waitcnt lgkmcnt(3)
	v_fma_f32 v133, v74, v30, v0
	v_fmac_f32_e32 v133, v75, v32
	v_fmac_f32_e32 v133, v76, v26
	v_fmac_f32_e32 v133, v77, v28
	s_waitcnt lgkmcnt(2)
	v_fmac_f32_e32 v133, v78, v22
	v_fmac_f32_e32 v133, v79, v24
	v_fmac_f32_e32 v133, v80, v18
	v_fmac_f32_e32 v133, v81, v20
	s_waitcnt lgkmcnt(1)
	v_fmac_f32_e32 v133, v134, v16
	v_fmac_f32_e32 v133, v135, v14
	v_fmac_f32_e32 v133, v136, v10
	v_fma_f32 v142, v74, v31, v1
	v_fmac_f32_e32 v133, v137, v12
	v_fmac_f32_e32 v142, v75, v33
	s_waitcnt lgkmcnt(0)
	v_fmac_f32_e32 v133, v138, v8
	v_fmac_f32_e32 v142, v76, v27
	v_fmac_f32_e32 v133, v139, v6
	v_fmac_f32_e32 v142, v77, v29
	v_fmac_f32_e32 v133, v140, v4
	v_fmac_f32_e32 v142, v78, v23
	v_fmac_f32_e32 v133, v141, v2
	v_fmac_f32_e32 v142, v79, v25
	v_mul_f32_e64 v75, |v133|, s90
	v_fmac_f32_e32 v142, v80, v19
	v_exp_f32_e32 v75, v75
	v_fmac_f32_e32 v142, v81, v21
	v_fmac_f32_e32 v142, v134, v17
	v_fmac_f32_e32 v142, v135, v15
	v_fmac_f32_e32 v142, v136, v11
	v_add_f32_e32 v75, 1.0, v75
	v_fmac_f32_e32 v142, v137, v13
	v_cmp_gt_f32_e64 s[62:63], s92, v75
	v_fmac_f32_e32 v142, v138, v9
	v_fmac_f32_e32 v142, v139, v7
	v_cndmask_b32_e64 v76, 0, 32, s[62:63]
	v_ldexp_f32 v75, v75, v76
	v_fmac_f32_e32 v142, v140, v5
	v_log_f32_e32 v75, v75
	v_fmac_f32_e32 v142, v141, v3
	v_mul_f32_e64 v77, |v142|, s90
	v_exp_f32_e32 v77, v77
	v_mul_f32_e32 v76, 0x3f317217, v75
	v_fma_f32 v76, v75, s41, -v76
	v_fmac_f32_e32 v76, 0x3377d1cf, v75
	v_fmac_f32_e32 v76, 0x3f317217, v75
	v_cmp_lt_f32_e64 s[64:65], |v75|, s68
	v_add_f32_e32 v77, 1.0, v77
	v_min_f32_e32 v74, 0, v133
	v_cndmask_b32_e64 v75, v75, v76, s[64:65]
	v_cndmask_b32_e64 v76, 0, v187, s[62:63]
	v_cmp_gt_f32_e64 s[62:63], s92, v77
	v_sub_f32_e32 v76, v75, v76
	v_min_f32_e32 v75, 0, v142
	v_cndmask_b32_e64 v78, 0, 32, s[62:63]
	v_ldexp_f32 v77, v77, v78
	v_log_f32_e32 v77, v77
	s_nop 0
	v_mul_f32_e32 v78, 0x3f317217, v77
	v_fma_f32 v78, v77, s41, -v78
	v_fmac_f32_e32 v78, 0x3377d1cf, v77
	v_fmac_f32_e32 v78, 0x3f317217, v77
	v_cmp_lt_f32_e64 s[64:65], |v77|, s68
	s_nop 1
	v_cndmask_b32_e64 v77, v77, v78, s[64:65]
	v_cndmask_b32_e64 v78, 0, v187, s[62:63]
	v_sub_f32_e32 v77, v77, v78
	v_sub_u32_e32 v78, 63, v86
	v_cndmask_b32_e32 v78, v78, v86, vcc
	v_lshl_add_u32 v133, v78, 7, s10
	ds_read_b128 v[78:81], v133
	ds_read_b128 v[134:137], v133 offset:16
	ds_read_b128 v[138:141], v133 offset:32
	ds_read_b128 v[142:145], v133 offset:48
	s_waitcnt lgkmcnt(3)
	v_fma_f32 v133, v78, v30, v0
	v_fmac_f32_e32 v133, v79, v32
	v_fmac_f32_e32 v133, v80, v26
	v_fmac_f32_e32 v133, v81, v28
	s_waitcnt lgkmcnt(2)
	v_fmac_f32_e32 v133, v134, v22
	v_fmac_f32_e32 v133, v135, v24
	v_fmac_f32_e32 v133, v136, v18
	v_fmac_f32_e32 v133, v137, v20
	s_waitcnt lgkmcnt(1)
	v_fmac_f32_e32 v133, v138, v16
	v_fmac_f32_e32 v133, v139, v14
	v_fmac_f32_e32 v133, v140, v10
	v_fma_f32 v146, v78, v31, v1
	v_fmac_f32_e32 v133, v141, v12
	v_fmac_f32_e32 v146, v79, v33
	s_waitcnt lgkmcnt(0)
	v_fmac_f32_e32 v133, v142, v8
	v_fmac_f32_e32 v146, v80, v27
	v_fmac_f32_e32 v133, v143, v6
	v_fmac_f32_e32 v146, v81, v29
	v_fmac_f32_e32 v133, v144, v4
	v_fmac_f32_e32 v146, v134, v23
	v_fmac_f32_e32 v133, v145, v2
	v_fmac_f32_e32 v146, v135, v25
	v_mul_f32_e64 v79, |v133|, s90
	v_fmac_f32_e32 v146, v136, v19
	v_exp_f32_e32 v79, v79
	v_fmac_f32_e32 v146, v137, v21
	v_fmac_f32_e32 v146, v138, v17
	v_fmac_f32_e32 v146, v139, v15
	v_fmac_f32_e32 v146, v140, v11
	v_add_f32_e32 v79, 1.0, v79
	v_fmac_f32_e32 v146, v141, v13
	v_cmp_gt_f32_e64 s[62:63], s92, v79
	v_fmac_f32_e32 v146, v142, v9
	v_fmac_f32_e32 v146, v143, v7
	v_cndmask_b32_e64 v80, 0, 32, s[62:63]
	v_ldexp_f32 v79, v79, v80
	v_fmac_f32_e32 v146, v144, v5
	v_log_f32_e32 v79, v79
	v_fmac_f32_e32 v146, v145, v3
	v_mul_f32_e64 v81, |v146|, s90
	v_exp_f32_e32 v81, v81
	v_mul_f32_e32 v80, 0x3f317217, v79
	v_fma_f32 v80, v79, s41, -v80
	v_fmac_f32_e32 v80, 0x3377d1cf, v79
	v_fmac_f32_e32 v80, 0x3f317217, v79
	v_cmp_lt_f32_e64 s[64:65], |v79|, s68
	v_add_f32_e32 v81, 1.0, v81
	v_min_f32_e32 v78, 0, v133
	v_cndmask_b32_e64 v79, v79, v80, s[64:65]
	v_cndmask_b32_e64 v80, 0, v187, s[62:63]
	v_cmp_gt_f32_e64 s[62:63], s92, v81
	v_sub_f32_e32 v80, v79, v80
	v_min_f32_e32 v79, 0, v146
	v_cndmask_b32_e64 v133, 0, 32, s[62:63]
	v_ldexp_f32 v81, v81, v133
	v_log_f32_e32 v81, v81
	s_nop 0
	v_mul_f32_e32 v133, 0x3f317217, v81
	v_fma_f32 v133, v81, s41, -v133
	v_fmac_f32_e32 v133, 0x3377d1cf, v81
	v_fmac_f32_e32 v133, 0x3f317217, v81
	v_cmp_lt_f32_e64 s[64:65], |v81|, s68
	s_nop 1
	v_cndmask_b32_e64 v81, v81, v133, s[64:65]
	v_cndmask_b32_e64 v133, 0, v187, s[62:63]
	v_sub_f32_e32 v81, v81, v133
	v_sub_u32_e32 v133, 63, v83
	v_cndmask_b32_e32 v133, v133, v83, vcc
	v_lshl_add_u32 v133, v133, 7, s10
	ds_read_b128 v[134:137], v133
	ds_read_b128 v[138:141], v133 offset:16
	ds_read_b128 v[142:145], v133 offset:32
	ds_read_b128 v[154:157], v133 offset:48
	s_or_b32 s10, s12, s0
	s_waitcnt lgkmcnt(3)
	v_fma_f32 v0, v134, v30, v0
	v_fmac_f32_e32 v0, v135, v32
	v_fmac_f32_e32 v0, v136, v26
	v_fmac_f32_e32 v0, v137, v28
	s_waitcnt lgkmcnt(2)
	v_fmac_f32_e32 v0, v138, v22
	v_fmac_f32_e32 v0, v139, v24
	v_fmac_f32_e32 v0, v140, v18
	v_fmac_f32_e32 v0, v141, v20
	v_fmac_f32_e32 v1, v134, v31
	s_waitcnt lgkmcnt(1)
	v_fmac_f32_e32 v0, v142, v16
	v_fmac_f32_e32 v1, v135, v33
	v_fmac_f32_e32 v0, v143, v14
	v_fmac_f32_e32 v1, v136, v27
	v_fmac_f32_e32 v0, v144, v10
	v_fmac_f32_e32 v1, v137, v29
	v_fmac_f32_e32 v0, v145, v12
	v_fmac_f32_e32 v1, v138, v23
	s_waitcnt lgkmcnt(0)
	v_fmac_f32_e32 v0, v154, v8
	v_fmac_f32_e32 v1, v139, v25
	v_fmac_f32_e32 v0, v155, v6
	v_fmac_f32_e32 v1, v140, v19
	v_fmac_f32_e32 v0, v156, v4
	v_fmac_f32_e32 v1, v141, v21
	v_fmac_f32_e32 v0, v157, v2
	v_fmac_f32_e32 v1, v142, v17
	v_min_f32_e32 v2, 0, v0
	v_mul_f32_e64 v0, |v0|, s90
	v_fmac_f32_e32 v1, v143, v15
	v_exp_f32_e32 v0, v0
	v_fmac_f32_e32 v1, v144, v11
	v_fmac_f32_e32 v1, v145, v13
	v_fmac_f32_e32 v1, v154, v9
	v_fmac_f32_e32 v1, v155, v7
	v_add_f32_e32 v0, 1.0, v0
	v_fmac_f32_e32 v1, v156, v5
	v_cmp_gt_f32_e32 vcc, s92, v0
	v_fmac_f32_e32 v1, v157, v3
	v_pk_fma_f32 v[32:33], v[44:45], s[2:3], v[34:35] op_sel_hi:[1,0,1]
	v_cndmask_b32_e64 v3, 0, 32, vcc
	v_ldexp_f32 v0, v0, v3
	v_log_f32_e32 v0, v0
	v_pk_fma_f32 v[30:31], v[46:47], s[2:3], v[32:33] op_sel_hi:[1,0,1]
	v_add_u32_e32 v44, 0, v64
	s_ashr_i32 s11, s10, 31
	v_mul_f32_e32 v3, 0x3f317217, v0
	v_fma_f32 v3, v0, s41, -v3
	v_fmac_f32_e32 v3, 0x3377d1cf, v0
	v_fmac_f32_e32 v3, 0x3f317217, v0
	v_cmp_lt_f32_e64 s[62:63], |v0|, s68
	v_lshlrev_b32_e32 v45, 2, v127
	v_add_u32_e32 v18, 0, v45
	v_cndmask_b32_e64 v0, v0, v3, s[62:63]
	v_cndmask_b32_e32 v3, 0, v187, vcc
	v_sub_f32_e32 v0, v0, v3
	v_min_f32_e32 v3, 0, v1
	v_mul_f32_e64 v1, |v1|, s90
	v_exp_f32_e32 v1, v1
	s_movk_i32 s0, 0x2100
	v_add_f32_e32 v1, 1.0, v1
	v_cmp_gt_f32_e32 vcc, s92, v1
	s_nop 1
	v_cndmask_b32_e64 v4, 0, 32, vcc
	v_ldexp_f32 v1, v1, v4
	v_log_f32_e32 v1, v1
	s_nop 0
	v_mul_f32_e32 v4, 0x3f317217, v1
	v_fma_f32 v4, v1, s41, -v4
	v_fmac_f32_e32 v4, 0x3377d1cf, v1
	v_fmac_f32_e32 v4, 0x3f317217, v1
	v_cmp_lt_f32_e64 s[62:63], |v1|, s68
	s_nop 1
	v_cndmask_b32_e64 v1, v1, v4, s[62:63]
	v_cndmask_b32_e32 v4, 0, v187, vcc
	v_sub_f32_e32 v1, v1, v4
	v_pk_add_f32 v[4:5], v[48:49], v[50:51] neg_lo:[0,1] neg_hi:[0,1]
	v_pk_add_f32 v[0:1], v[2:3], v[0:1] neg_lo:[0,1] neg_hi:[0,1]
	v_pk_fma_f32 v[28:29], v[4:5], s[2:3], v[30:31] op_sel_hi:[1,0,1]
	v_pk_add_f32 v[4:5], v[52:53], v[54:55] neg_lo:[0,1] neg_hi:[0,1]
	v_cmp_lt_i32_e32 vcc, 0, v123
	v_pk_fma_f32 v[26:27], v[4:5], s[2:3], v[28:29] op_sel_hi:[1,0,1]
	v_pk_add_f32 v[4:5], v[56:57], v[58:59] neg_lo:[0,1] neg_hi:[0,1]
	v_lshlrev_b32_e32 v50, 7, v127
	v_pk_fma_f32 v[24:25], v[4:5], s[2:3], v[26:27] op_sel_hi:[1,0,1]
	v_pk_add_f32 v[4:5], v[60:61], v[62:63] neg_lo:[0,1] neg_hi:[0,1]
	s_nop 0
	v_pk_fma_f32 v[22:23], v[4:5], s[2:3], v[24:25] op_sel_hi:[1,0,1]
	v_pk_add_f32 v[4:5], v[66:67], v[68:69] neg_lo:[0,1] neg_hi:[0,1]
	s_nop 0
	v_pk_fma_f32 v[20:21], v[4:5], s[2:3], v[22:23] op_sel_hi:[1,0,1]
	v_pk_add_f32 v[4:5], v[70:71], v[72:73] neg_lo:[0,1] neg_hi:[0,1]
	s_nop 0
	v_pk_fma_f32 v[16:17], v[4:5], s[2:3], v[20:21] op_sel_hi:[1,0,1]
	v_pk_add_f32 v[4:5], v[74:75], v[76:77] neg_lo:[0,1] neg_hi:[0,1]
	s_nop 0
	v_pk_fma_f32 v[14:15], v[4:5], s[2:3], v[16:17] op_sel_hi:[1,0,1]
	v_pk_add_f32 v[4:5], v[78:79], v[80:81] neg_lo:[0,1] neg_hi:[0,1]
	s_nop 0
	v_pk_fma_f32 v[10:11], v[4:5], s[2:3], v[14:15] op_sel_hi:[1,0,1]
	s_nop 0
	v_pk_fma_f32 v[2:3], v[0:1], s[2:3], v[10:11] op_sel_hi:[1,0,1]
	v_add_u32_e32 v0, 0x21400, v44
	v_lshl_add_u32 v1, v123, 10, v0
	ds_write_b64 v1, v[2:3]
	s_waitcnt lgkmcnt(0)
	s_barrier
	ds_read2st64_b64 v[6:9], v0 offset1:2
	ds_read2st64_b64 v[46:49], v0 offset0:4 offset1:6
	s_lshl_b64 s[2:3], s[10:11], 15
	s_add_u32 s12, s23, s2
	s_addc_u32 s13, s6, s3
	s_waitcnt lgkmcnt(1)
	v_pk_add_f32 v[4:5], v[6:7], v[8:9]
	v_pk_add_f32 v[6:7], v[6:7], 0 op_sel_hi:[1,0]
	s_waitcnt lgkmcnt(0)
	v_pk_add_f32 v[0:1], v[4:5], v[46:47]
	v_cndmask_b32_e32 v7, 0, v7, vcc
	v_cndmask_b32_e32 v6, 0, v6, vcc
	v_cmp_lt_i32_e32 vcc, 1, v123
	v_pk_add_f32 v[8:9], v[8:9], v[6:7]
	v_pk_add_f32 v[0:1], v[0:1], v[48:49]
	v_cndmask_b32_e32 v7, v7, v9, vcc
	v_cndmask_b32_e32 v6, v6, v8, vcc
	v_cmp_lt_i32_e32 vcc, 2, v123
	v_pk_add_f32 v[8:9], v[46:47], v[6:7]
	v_lshlrev_b32_e32 v48, 16, v132
	v_cndmask_b32_e32 v13, v7, v9, vcc
	v_cndmask_b32_e32 v12, v6, v8, vcc
	v_pk_add_f32 v[42:43], v[42:43], v[12:13]
	v_mul_f32_e32 v6, 0x3fb8aa3b, v4
	v_pk_add_f32 v[46:47], v[42:43], v[4:5] neg_lo:[0,1] neg_hi:[0,1]
	v_pk_add_f32 v[42:43], v[4:5], v[42:43] neg_lo:[0,1] neg_hi:[0,1]
	v_mul_f32_e32 v19, 0x3fb8aa3b, v46
	v_exp_f32_e32 v46, v19
	v_mul_f32_e32 v19, 0x3fb8aa3b, v47
	v_exp_f32_e32 v47, v19
	v_mul_f32_e32 v19, 0x3fb8aa3b, v42
	v_exp_f32_e32 v42, v19
	v_mul_f32_e32 v19, 0x3fb8aa3b, v43
	v_exp_f32_e32 v8, v6
	v_mul_f32_e32 v6, 0x3fb8aa3b, v5
	v_exp_f32_e32 v43, v19
	v_exp_f32_e32 v9, v6
	v_pk_add_f32 v[6:7], v[0:1], v[4:5] neg_lo:[0,1] neg_hi:[0,1]
	v_and_b32_e32 v49, 0xffff0000, v132
	v_mul_f32_e32 v6, 0x3fb8aa3b, v6
	v_mul_f32_e32 v7, 0x3fb8aa3b, v7
	v_pk_mul_f32 v[46:47], v[46:47], v[48:49]
	v_exp_f32_e32 v6, v6
	v_exp_f32_e32 v7, v7
	s_add_u32 s14, s7, s2
	v_lshlrev_b32_e32 v48, 16, v131
	v_and_b32_e32 v49, 0xffff0000, v131
	v_cvt_pk_bf16_f32 v19, v46, v47
	s_addc_u32 s15, s58, s3
	v_pk_mul_f32 v[42:43], v[42:43], v[48:49]
	v_mad_u64_u32 v[48:49], s[2:3], v123, s0, v[18:19]
	v_cvt_pk_bf16_f32 v49, v42, v43
	v_pk_mul_f32 v[46:47], v[8:9], v[46:47]
	ds_write2st64_b32 v48, v19, v49 offset1:132
	v_cvt_pk_bf16_f32 v19, v46, v47
	v_lshl_or_b32 v46, v123, 13, v45
	v_ashrrev_i32_e32 v47, 31, v46
	v_pk_mul_f32 v[42:43], v[6:7], v[42:43]
	v_pk_add_f32 v[40:41], v[40:41], v[12:13]
	v_lshl_add_u64 v[46:47], s[12:13], 0, v[46:47]
	v_cvt_pk_bf16_f32 v48, v42, v43
	v_pk_add_f32 v[42:43], v[40:41], v[4:5] neg_lo:[0,1] neg_hi:[0,1]
	global_store_dword v[46:47], v19, off nt
	v_mul_f32_e32 v19, 0x3fb8aa3b, v42
	v_exp_f32_e32 v42, v19
	v_mul_f32_e32 v19, 0x3fb8aa3b, v43
	v_pk_add_f32 v[40:41], v[4:5], v[40:41] neg_lo:[0,1] neg_hi:[0,1]
	v_exp_f32_e32 v43, v19
	v_mul_f32_e32 v19, 0x3fb8aa3b, v40
	v_exp_f32_e32 v40, v19
	v_mul_f32_e32 v19, 0x3fb8aa3b, v41
	v_exp_f32_e32 v41, v19
	v_lshlrev_b32_e32 v46, 16, v130
	v_and_b32_e32 v47, 0xffff0000, v130
	v_pk_mul_f32 v[42:43], v[42:43], v[46:47]
	v_lshlrev_b32_e32 v46, 16, v129
	v_and_b32_e32 v47, 0xffff0000, v129
	v_pk_mul_f32 v[40:41], v[40:41], v[46:47]
	v_cvt_pk_bf16_f32 v46, v42, v43
	v_pk_mul_f32 v[42:43], v[8:9], v[42:43]
	v_mad_u64_u32 v[18:19], s[2:3], v128, s37, v[18:19]
	v_cvt_pk_bf16_f32 v47, v42, v43
	v_lshl_or_b32 v42, v128, 9, v45
	v_ashrrev_i32_e32 v43, 31, v42
	v_cvt_pk_bf16_f32 v19, v40, v41
	v_lshl_add_u64 v[42:43], s[12:13], 0, v[42:43]
	v_pk_mul_f32 v[40:41], v[6:7], v[40:41]
	v_pk_add_f32 v[38:39], v[38:39], v[12:13]
	global_store_dword v[42:43], v47, off nt
	v_cvt_pk_bf16_f32 v47, v40, v41
	v_pk_add_f32 v[40:41], v[38:39], v[4:5] neg_lo:[0,1] neg_hi:[0,1]
	v_pk_add_f32 v[38:39], v[4:5], v[38:39] neg_lo:[0,1] neg_hi:[0,1]
	v_mul_f32_e32 v40, 0x3fb8aa3b, v40
	v_mul_f32_e32 v41, 0x3fb8aa3b, v41
	v_exp_f32_e32 v40, v40
	v_exp_f32_e32 v41, v41
	v_mul_f32_e32 v38, 0x3fb8aa3b, v38
	v_mul_f32_e32 v39, 0x3fb8aa3b, v39
	v_exp_f32_e32 v38, v38
	v_exp_f32_e32 v39, v39
	v_lshlrev_b32_e32 v42, 16, v126
	v_and_b32_e32 v43, 0xffff0000, v126
	v_pk_mul_f32 v[40:41], v[40:41], v[42:43]
	v_lshlrev_b32_e32 v42, 16, v125
	v_and_b32_e32 v43, 0xffff0000, v125
	v_pk_mul_f32 v[38:39], v[38:39], v[42:43]
	v_cvt_pk_bf16_f32 v42, v40, v41
	ds_write2_b32 v18, v46, v42 offset1:132
	v_cvt_pk_bf16_f32 v42, v38, v39
	v_add_u32_e32 v43, 0x8400, v18
	v_pk_mul_f32 v[40:41], v[8:9], v[40:41]
	ds_write2_b32 v43, v19, v42 offset1:132
	v_cvt_pk_bf16_f32 v19, v40, v41
	v_lshl_or_b32 v40, v124, 9, v45
	v_ashrrev_i32_e32 v41, 31, v40
	v_lshl_add_u64 v[40:41], s[12:13], 0, v[40:41]
	v_pk_mul_f32 v[38:39], v[6:7], v[38:39]
	v_pk_add_f32 v[36:37], v[36:37], v[12:13]
	global_store_dword v[40:41], v19, off nt
	v_cvt_pk_bf16_f32 v19, v38, v39
	v_pk_add_f32 v[38:39], v[36:37], v[4:5] neg_lo:[0,1] neg_hi:[0,1]
	v_pk_add_f32 v[36:37], v[4:5], v[36:37] neg_lo:[0,1] neg_hi:[0,1]
	v_mul_f32_e32 v38, 0x3fb8aa3b, v38
	v_mul_f32_e32 v39, 0x3fb8aa3b, v39
	v_exp_f32_e32 v38, v38
	v_exp_f32_e32 v39, v39
	v_mul_f32_e32 v36, 0x3fb8aa3b, v36
	v_mul_f32_e32 v37, 0x3fb8aa3b, v37
	v_exp_f32_e32 v36, v36
	v_exp_f32_e32 v37, v37
	v_lshlrev_b32_e32 v40, 16, v122
	v_and_b32_e32 v41, 0xffff0000, v122
	v_pk_mul_f32 v[38:39], v[38:39], v[40:41]
	v_lshlrev_b32_e32 v40, 16, v121
	v_and_b32_e32 v41, 0xffff0000, v121
	v_pk_mul_f32 v[36:37], v[36:37], v[40:41]
	v_cvt_pk_bf16_f32 v40, v38, v39
	v_pk_mul_f32 v[38:39], v[8:9], v[38:39]
	v_cvt_pk_bf16_f32 v41, v36, v37
	v_cvt_pk_bf16_f32 v42, v38, v39
	v_lshl_or_b32 v38, v120, 9, v45
	v_ashrrev_i32_e32 v39, 31, v38
	v_lshl_add_u64 v[38:39], s[12:13], 0, v[38:39]
	v_pk_mul_f32 v[36:37], v[6:7], v[36:37]
	v_pk_add_f32 v[34:35], v[34:35], v[12:13]
	global_store_dword v[38:39], v42, off nt
	v_cvt_pk_bf16_f32 v42, v36, v37
	v_pk_add_f32 v[36:37], v[34:35], v[4:5] neg_lo:[0,1] neg_hi:[0,1]
	v_pk_add_f32 v[34:35], v[4:5], v[34:35] neg_lo:[0,1] neg_hi:[0,1]
	v_mul_f32_e32 v36, 0x3fb8aa3b, v36
	v_mul_f32_e32 v37, 0x3fb8aa3b, v37
	v_exp_f32_e32 v36, v36
	v_exp_f32_e32 v37, v37
	v_mul_f32_e32 v34, 0x3fb8aa3b, v34
	v_mul_f32_e32 v35, 0x3fb8aa3b, v35
	v_exp_f32_e32 v34, v34
	v_exp_f32_e32 v35, v35
	v_lshlrev_b32_e32 v38, 16, v119
	v_and_b32_e32 v39, 0xffff0000, v119
	v_pk_mul_f32 v[36:37], v[36:37], v[38:39]
	v_lshlrev_b32_e32 v38, 16, v118
	v_and_b32_e32 v39, 0xffff0000, v118
	v_pk_mul_f32 v[34:35], v[34:35], v[38:39]
	v_cvt_pk_bf16_f32 v38, v36, v37
	v_add_u32_e32 v39, 0x400, v18
	ds_write2_b32 v39, v40, v38 offset0:8 offset1:140
	v_cvt_pk_bf16_f32 v38, v34, v35
	v_add_u32_e32 v39, 0x8800, v18
	v_pk_mul_f32 v[36:37], v[8:9], v[36:37]
	ds_write2_b32 v39, v41, v38 offset0:8 offset1:140
	v_cvt_pk_bf16_f32 v38, v36, v37
	v_lshl_or_b32 v36, v117, 9, v45
	v_ashrrev_i32_e32 v37, 31, v36
	v_lshl_add_u64 v[36:37], s[12:13], 0, v[36:37]
	v_pk_mul_f32 v[34:35], v[6:7], v[34:35]
	v_pk_add_f32 v[32:33], v[32:33], v[12:13]
	global_store_dword v[36:37], v38, off nt
	v_cvt_pk_bf16_f32 v38, v34, v35
	v_pk_add_f32 v[34:35], v[32:33], v[4:5] neg_lo:[0,1] neg_hi:[0,1]
	v_pk_add_f32 v[32:33], v[4:5], v[32:33] neg_lo:[0,1] neg_hi:[0,1]
	v_mul_f32_e32 v34, 0x3fb8aa3b, v34
	v_mul_f32_e32 v35, 0x3fb8aa3b, v35
	v_exp_f32_e32 v34, v34
	v_exp_f32_e32 v35, v35
	v_mul_f32_e32 v32, 0x3fb8aa3b, v32
	v_mul_f32_e32 v33, 0x3fb8aa3b, v33
	v_exp_f32_e32 v32, v32
	v_exp_f32_e32 v33, v33
	v_lshlrev_b32_e32 v36, 16, v116
	v_and_b32_e32 v37, 0xffff0000, v116
	v_pk_mul_f32 v[34:35], v[34:35], v[36:37]
	v_lshlrev_b32_e32 v36, 16, v115
	v_and_b32_e32 v37, 0xffff0000, v115
	v_pk_mul_f32 v[32:33], v[32:33], v[36:37]
	v_cvt_pk_bf16_f32 v36, v34, v35
	v_cvt_pk_bf16_f32 v37, v32, v33
	v_pk_mul_f32 v[34:35], v[8:9], v[34:35]
	ds_write_b32 v18, v37 offset:35904
	v_cvt_pk_bf16_f32 v37, v34, v35
	v_lshl_or_b32 v34, v114, 9, v45
	v_ashrrev_i32_e32 v35, 31, v34
	v_lshl_add_u64 v[34:35], s[12:13], 0, v[34:35]
	v_pk_mul_f32 v[32:33], v[6:7], v[32:33]
	v_pk_add_f32 v[30:31], v[30:31], v[12:13]
	global_store_dword v[34:35], v37, off nt
	v_cvt_pk_bf16_f32 v37, v32, v33
	v_pk_add_f32 v[32:33], v[30:31], v[4:5] neg_lo:[0,1] neg_hi:[0,1]
	v_pk_add_f32 v[30:31], v[4:5], v[30:31] neg_lo:[0,1] neg_hi:[0,1]
	v_mul_f32_e32 v32, 0x3fb8aa3b, v32
	v_mul_f32_e32 v33, 0x3fb8aa3b, v33
	v_exp_f32_e32 v32, v32
	v_exp_f32_e32 v33, v33
	v_mul_f32_e32 v30, 0x3fb8aa3b, v30
	v_mul_f32_e32 v31, 0x3fb8aa3b, v31
	v_exp_f32_e32 v30, v30
	v_exp_f32_e32 v31, v31
	v_lshlrev_b32_e32 v34, 16, v113
	v_and_b32_e32 v35, 0xffff0000, v113
	v_pk_mul_f32 v[32:33], v[32:33], v[34:35]
	v_lshlrev_b32_e32 v34, 16, v112
	v_and_b32_e32 v35, 0xffff0000, v112
	v_pk_mul_f32 v[30:31], v[30:31], v[34:35]
	v_cvt_pk_bf16_f32 v34, v32, v33
	v_add_u32_e32 v35, 0x800, v18
	ds_write2_b32 v35, v36, v34 offset0:16 offset1:148
	v_cvt_pk_bf16_f32 v34, v30, v31
	v_pk_mul_f32 v[30:31], v[6:7], v[30:31]
	v_pk_add_f32 v[28:29], v[28:29], v[12:13]
	v_cvt_pk_bf16_f32 v39, v30, v31
	v_pk_add_f32 v[30:31], v[28:29], v[4:5] neg_lo:[0,1] neg_hi:[0,1]
	v_pk_mul_f32 v[32:33], v[8:9], v[32:33]
	v_mul_f32_e32 v30, 0x3fb8aa3b, v30
	v_mul_f32_e32 v31, 0x3fb8aa3b, v31
	v_pk_add_f32 v[28:29], v[4:5], v[28:29] neg_lo:[0,1] neg_hi:[0,1]
	v_cvt_pk_bf16_f32 v35, v32, v33
	v_lshl_or_b32 v32, v111, 9, v45
	v_exp_f32_e32 v30, v30
	v_exp_f32_e32 v31, v31
	v_mul_f32_e32 v28, 0x3fb8aa3b, v28
	v_mul_f32_e32 v29, 0x3fb8aa3b, v29
	v_ashrrev_i32_e32 v33, 31, v32
	v_exp_f32_e32 v28, v28
	v_exp_f32_e32 v29, v29
	v_lshl_add_u64 v[32:33], s[12:13], 0, v[32:33]
	global_store_dword v[32:33], v35, off nt
	v_lshlrev_b32_e32 v32, 16, v110
	v_and_b32_e32 v33, 0xffff0000, v110
	v_pk_mul_f32 v[30:31], v[30:31], v[32:33]
	v_lshlrev_b32_e32 v32, 16, v109
	v_and_b32_e32 v33, 0xffff0000, v109
	v_pk_mul_f32 v[28:29], v[28:29], v[32:33]
	v_cvt_pk_bf16_f32 v40, v30, v31
	v_cvt_pk_bf16_f32 v32, v28, v29
	v_add_u32_e32 v33, 0x8e00, v18
	v_pk_mul_f32 v[30:31], v[8:9], v[30:31]
	ds_write2_b32 v33, v34, v32 offset0:20 offset1:152
	v_cvt_pk_bf16_f32 v32, v30, v31
	v_lshl_or_b32 v30, v108, 9, v45
	v_ashrrev_i32_e32 v31, 31, v30
	v_pk_mul_f32 v[28:29], v[6:7], v[28:29]
	v_lshl_add_u64 v[30:31], s[12:13], 0, v[30:31]
	v_cvt_pk_bf16_f32 v28, v28, v29
	v_lshlrev_b32_e32 v29, 16, v47
	global_store_dword v[30:31], v32, off nt
	v_and_or_b32 v30, v48, s35, v29
	v_lshlrev_b32_e32 v29, 16, v42
	v_and_or_b32 v31, v19, s35, v29
	v_lshlrev_b32_e32 v29, 16, v37
	v_lshrrev_b32_e32 v19, 16, v19
	v_and_or_b32 v32, v38, s35, v29
	v_lshlrev_b32_e32 v29, 16, v28
	v_and_or_b32 v35, v42, s88, v19
	v_lshrrev_b32_e32 v19, 16, v38
	v_add_lshl_u32 v38, v50, v104, 1
	v_and_or_b32 v33, v39, s35, v29
	v_lshrrev_b32_e32 v29, 16, v48
	v_and_or_b32 v36, v37, s88, v19
	v_lshrrev_b32_e32 v19, 16, v39
	v_ashrrev_i32_e32 v39, 31, v38
	v_and_or_b32 v34, v47, s88, v29
	v_and_or_b32 v37, v28, s88, v19
	v_lshl_add_u64 v[28:29], s[14:15], 0, v[38:39]
	v_pk_add_f32 v[26:27], v[26:27], v[12:13]
	global_store_dwordx4 v[28:29], v[30:33], off
	v_pk_add_f32 v[24:25], v[24:25], v[12:13]
	v_pk_add_f32 v[22:23], v[22:23], v[12:13]
	v_pk_add_f32 v[32:33], v[26:27], v[4:5] neg_lo:[0,1] neg_hi:[0,1]
	v_pk_add_f32 v[26:27], v[4:5], v[26:27] neg_lo:[0,1] neg_hi:[0,1]
	v_mul_f32_e32 v19, 0x3fb8aa3b, v32
	v_exp_f32_e32 v32, v19
	v_mul_f32_e32 v19, 0x3fb8aa3b, v33
	v_exp_f32_e32 v33, v19
	v_mul_f32_e32 v19, 0x3fb8aa3b, v26
	v_add_u32_e32 v30, 0x80, v38
	v_exp_f32_e32 v26, v19
	v_mul_f32_e32 v19, 0x3fb8aa3b, v27
	v_ashrrev_i32_e32 v31, 31, v30
	v_exp_f32_e32 v27, v19
	v_lshl_add_u64 v[30:31], s[14:15], 0, v[30:31]
	global_store_dwordx4 v[30:31], v[34:37], off
	v_pk_add_f32 v[20:21], v[20:21], v[12:13]
	v_pk_add_f32 v[16:17], v[16:17], v[12:13]
	v_lshlrev_b32_e32 v34, 16, v107
	v_and_b32_e32 v35, 0xffff0000, v107
	v_pk_mul_f32 v[32:33], v[32:33], v[34:35]
	v_lshlrev_b32_e32 v34, 16, v106
	v_and_b32_e32 v35, 0xffff0000, v106
	v_pk_mul_f32 v[26:27], v[26:27], v[34:35]
	v_cvt_pk_bf16_f32 v19, v32, v33
	v_add_u32_e32 v34, 0xc00, v18
	v_pk_mul_f32 v[32:33], v[8:9], v[32:33]
	ds_write2_b32 v34, v40, v19 offset0:24 offset1:156
	v_cvt_pk_bf16_f32 v34, v32, v33
	v_lshl_or_b32 v32, v105, 9, v45
	v_ashrrev_i32_e32 v33, 31, v32
	v_cvt_pk_bf16_f32 v19, v26, v27
	v_lshl_add_u64 v[32:33], s[12:13], 0, v[32:33]
	v_pk_mul_f32 v[26:27], v[6:7], v[26:27]
	global_store_dword v[32:33], v34, off nt
	v_cvt_pk_bf16_f32 v34, v26, v27
	v_pk_add_f32 v[26:27], v[24:25], v[4:5] neg_lo:[0,1] neg_hi:[0,1]
	v_pk_add_f32 v[24:25], v[4:5], v[24:25] neg_lo:[0,1] neg_hi:[0,1]
	v_mul_f32_e32 v26, 0x3fb8aa3b, v26
	v_mul_f32_e32 v27, 0x3fb8aa3b, v27
	v_exp_f32_e32 v26, v26
	v_exp_f32_e32 v27, v27
	v_mul_f32_e32 v24, 0x3fb8aa3b, v24
	v_mul_f32_e32 v25, 0x3fb8aa3b, v25
	v_exp_f32_e32 v24, v24
	v_exp_f32_e32 v25, v25
	v_lshlrev_b32_e32 v32, 16, v103
	v_and_b32_e32 v33, 0xffff0000, v103
	v_pk_mul_f32 v[26:27], v[26:27], v[32:33]
	v_lshlrev_b32_e32 v32, 16, v102
	v_and_b32_e32 v33, 0xffff0000, v102
	v_pk_mul_f32 v[24:25], v[24:25], v[32:33]
	v_cvt_pk_bf16_f32 v32, v26, v27
	v_cvt_pk_bf16_f32 v33, v24, v25
	v_add_u32_e32 v35, 0x9200, v18
	v_pk_mul_f32 v[26:27], v[8:9], v[26:27]
	ds_write2_b32 v35, v19, v33 offset0:28 offset1:160
	v_cvt_pk_bf16_f32 v19, v26, v27
	v_lshl_or_b32 v26, v101, 9, v45
	v_ashrrev_i32_e32 v27, 31, v26
	v_lshl_add_u64 v[26:27], s[12:13], 0, v[26:27]
	v_pk_mul_f32 v[24:25], v[6:7], v[24:25]
	global_store_dword v[26:27], v19, off nt
	v_cvt_pk_bf16_f32 v19, v24, v25
	v_pk_add_f32 v[24:25], v[22:23], v[4:5] neg_lo:[0,1] neg_hi:[0,1]
	v_pk_add_f32 v[22:23], v[4:5], v[22:23] neg_lo:[0,1] neg_hi:[0,1]
	v_mul_f32_e32 v24, 0x3fb8aa3b, v24
	v_mul_f32_e32 v25, 0x3fb8aa3b, v25
	v_exp_f32_e32 v24, v24
	v_exp_f32_e32 v25, v25
	v_mul_f32_e32 v22, 0x3fb8aa3b, v22
	v_mul_f32_e32 v23, 0x3fb8aa3b, v23
	v_exp_f32_e32 v22, v22
	v_exp_f32_e32 v23, v23
	v_lshlrev_b32_e32 v26, 16, v100
	v_and_b32_e32 v27, 0xffff0000, v100
	v_pk_mul_f32 v[24:25], v[24:25], v[26:27]
	v_lshlrev_b32_e32 v26, 16, v99
	v_and_b32_e32 v27, 0xffff0000, v99
	v_pk_mul_f32 v[22:23], v[22:23], v[26:27]
	v_cvt_pk_bf16_f32 v26, v24, v25
	v_add_u32_e32 v27, 0x1000, v18
	v_pk_mul_f32 v[24:25], v[8:9], v[24:25]
	ds_write2_b32 v27, v32, v26 offset0:32 offset1:164
	v_cvt_pk_bf16_f32 v27, v24, v25
	v_lshl_or_b32 v24, v98, 9, v45
	v_ashrrev_i32_e32 v25, 31, v24
	v_cvt_pk_bf16_f32 v26, v22, v23
	v_lshl_add_u64 v[24:25], s[12:13], 0, v[24:25]
	v_pk_mul_f32 v[22:23], v[6:7], v[22:23]
	global_store_dword v[24:25], v27, off nt
	v_cvt_pk_bf16_f32 v27, v22, v23
	v_pk_add_f32 v[22:23], v[20:21], v[4:5] neg_lo:[0,1] neg_hi:[0,1]
	v_pk_add_f32 v[20:21], v[4:5], v[20:21] neg_lo:[0,1] neg_hi:[0,1]
	v_mul_f32_e32 v22, 0x3fb8aa3b, v22
	v_mul_f32_e32 v23, 0x3fb8aa3b, v23
	v_exp_f32_e32 v22, v22
	v_exp_f32_e32 v23, v23
	v_mul_f32_e32 v20, 0x3fb8aa3b, v20
	v_mul_f32_e32 v21, 0x3fb8aa3b, v21
	v_exp_f32_e32 v20, v20
	v_exp_f32_e32 v21, v21
	v_lshlrev_b32_e32 v24, 16, v97
	v_and_b32_e32 v25, 0xffff0000, v97
	v_pk_mul_f32 v[22:23], v[22:23], v[24:25]
	v_lshlrev_b32_e32 v24, 16, v96
	v_and_b32_e32 v25, 0xffff0000, v96
	v_pk_mul_f32 v[20:21], v[20:21], v[24:25]
	v_cvt_pk_bf16_f32 v24, v22, v23
	v_cvt_pk_bf16_f32 v25, v20, v21
	v_add_u32_e32 v32, 0x9600, v18
	v_pk_mul_f32 v[22:23], v[8:9], v[22:23]
	ds_write2_b32 v32, v26, v25 offset0:36 offset1:168
	v_cvt_pk_bf16_f32 v25, v22, v23
	v_lshl_or_b32 v22, v95, 9, v45
	v_ashrrev_i32_e32 v23, 31, v22
	v_lshl_add_u64 v[22:23], s[12:13], 0, v[22:23]
	v_pk_mul_f32 v[20:21], v[6:7], v[20:21]
	global_store_dword v[22:23], v25, off nt
	v_cvt_pk_bf16_f32 v25, v20, v21
	v_pk_add_f32 v[20:21], v[16:17], v[4:5] neg_lo:[0,1] neg_hi:[0,1]
	v_pk_add_f32 v[16:17], v[4:5], v[16:17] neg_lo:[0,1] neg_hi:[0,1]
	v_mul_f32_e32 v20, 0x3fb8aa3b, v20
	v_mul_f32_e32 v21, 0x3fb8aa3b, v21
	v_exp_f32_e32 v20, v20
	v_exp_f32_e32 v21, v21
	v_mul_f32_e32 v16, 0x3fb8aa3b, v16
	v_mul_f32_e32 v17, 0x3fb8aa3b, v17
	v_exp_f32_e32 v16, v16
	v_exp_f32_e32 v17, v17
	v_lshlrev_b32_e32 v22, 16, v94
	v_and_b32_e32 v23, 0xffff0000, v94
	v_pk_mul_f32 v[20:21], v[20:21], v[22:23]
	v_lshlrev_b32_e32 v22, 16, v93
	v_and_b32_e32 v23, 0xffff0000, v93
	v_pk_mul_f32 v[16:17], v[16:17], v[22:23]
	v_cvt_pk_bf16_f32 v22, v20, v21
	v_add_u32_e32 v23, 0x1400, v18
	v_pk_mul_f32 v[20:21], v[8:9], v[20:21]
	ds_write2_b32 v23, v24, v22 offset0:40 offset1:172
	v_cvt_pk_bf16_f32 v23, v20, v21
	v_lshl_or_b32 v20, v92, 9, v45
	v_ashrrev_i32_e32 v21, 31, v20
	v_cvt_pk_bf16_f32 v22, v16, v17
	v_lshl_add_u64 v[20:21], s[12:13], 0, v[20:21]
	v_pk_mul_f32 v[16:17], v[6:7], v[16:17]
	v_pk_add_f32 v[14:15], v[12:13], v[14:15]
	global_store_dword v[20:21], v23, off nt
	v_cvt_pk_bf16_f32 v23, v16, v17
	v_pk_add_f32 v[16:17], v[14:15], v[4:5] neg_lo:[0,1] neg_hi:[0,1]
	v_pk_add_f32 v[14:15], v[4:5], v[14:15] neg_lo:[0,1] neg_hi:[0,1]
	v_mul_f32_e32 v16, 0x3fb8aa3b, v16
	v_mul_f32_e32 v17, 0x3fb8aa3b, v17
	v_exp_f32_e32 v16, v16
	v_exp_f32_e32 v17, v17
	v_mul_f32_e32 v14, 0x3fb8aa3b, v14
	v_mul_f32_e32 v15, 0x3fb8aa3b, v15
	v_exp_f32_e32 v14, v14
	v_exp_f32_e32 v15, v15
	v_lshlrev_b32_e32 v20, 16, v91
	v_and_b32_e32 v21, 0xffff0000, v91
	v_pk_mul_f32 v[16:17], v[16:17], v[20:21]
	v_lshlrev_b32_e32 v20, 16, v90
	v_and_b32_e32 v21, 0xffff0000, v90
	v_pk_mul_f32 v[14:15], v[14:15], v[20:21]
	v_cvt_pk_bf16_f32 v20, v16, v17
	v_cvt_pk_bf16_f32 v21, v14, v15
	v_add_u32_e32 v24, 0x9a00, v18
	v_pk_mul_f32 v[16:17], v[8:9], v[16:17]
	ds_write2_b32 v24, v22, v21 offset0:44 offset1:176
	v_cvt_pk_bf16_f32 v21, v16, v17
	v_lshl_or_b32 v16, v89, 9, v45
	v_ashrrev_i32_e32 v17, 31, v16
	v_lshl_add_u64 v[16:17], s[12:13], 0, v[16:17]
	v_pk_mul_f32 v[14:15], v[6:7], v[14:15]
	v_pk_add_f32 v[10:11], v[12:13], v[10:11]
	global_store_dword v[16:17], v21, off nt
	v_cvt_pk_bf16_f32 v21, v14, v15
	v_pk_add_f32 v[14:15], v[10:11], v[4:5] neg_lo:[0,1] neg_hi:[0,1]
	v_pk_add_f32 v[10:11], v[4:5], v[10:11] neg_lo:[0,1] neg_hi:[0,1]
	v_mul_f32_e32 v14, 0x3fb8aa3b, v14
	v_mul_f32_e32 v15, 0x3fb8aa3b, v15
	v_exp_f32_e32 v14, v14
	v_exp_f32_e32 v15, v15
	v_mul_f32_e32 v10, 0x3fb8aa3b, v10
	v_mul_f32_e32 v11, 0x3fb8aa3b, v11
	v_exp_f32_e32 v10, v10
	v_exp_f32_e32 v11, v11
	v_lshlrev_b32_e32 v16, 16, v88
	v_and_b32_e32 v17, 0xffff0000, v88
	v_pk_mul_f32 v[14:15], v[14:15], v[16:17]
	v_lshlrev_b32_e32 v16, 16, v87
	v_and_b32_e32 v17, 0xffff0000, v87
	v_pk_mul_f32 v[10:11], v[10:11], v[16:17]
	v_cvt_pk_bf16_f32 v16, v14, v15
	v_add_u32_e32 v17, 0x1800, v18
	v_pk_mul_f32 v[14:15], v[8:9], v[14:15]
	ds_write2_b32 v17, v20, v16 offset0:48 offset1:180
	v_cvt_pk_bf16_f32 v17, v14, v15
	v_lshl_or_b32 v14, v86, 9, v45
	v_ashrrev_i32_e32 v15, 31, v14
	v_cvt_pk_bf16_f32 v16, v10, v11
	v_lshl_add_u64 v[14:15], s[12:13], 0, v[14:15]
	v_pk_mul_f32 v[10:11], v[6:7], v[10:11]
	v_pk_add_f32 v[2:3], v[12:13], v[2:3]
	global_store_dword v[14:15], v17, off nt
	v_cvt_pk_bf16_f32 v14, v10, v11
	v_pk_add_f32 v[10:11], v[2:3], v[4:5] neg_lo:[0,1] neg_hi:[0,1]
	v_pk_add_f32 v[2:3], v[4:5], v[2:3] neg_lo:[0,1] neg_hi:[0,1]
	v_mul_f32_e32 v10, 0x3fb8aa3b, v10
	v_mul_f32_e32 v11, 0x3fb8aa3b, v11
	v_exp_f32_e32 v10, v10
	v_exp_f32_e32 v11, v11
	v_mul_f32_e32 v2, 0x3fb8aa3b, v2
	v_mul_f32_e32 v3, 0x3fb8aa3b, v3
	v_exp_f32_e32 v2, v2
	v_exp_f32_e32 v3, v3
	v_lshlrev_b32_e32 v4, 16, v85
	v_and_b32_e32 v5, 0xffff0000, v85
	v_pk_mul_f32 v[4:5], v[10:11], v[4:5]
	v_lshlrev_b32_e32 v10, 16, v84
	v_and_b32_e32 v11, 0xffff0000, v84
	v_pk_mul_f32 v[2:3], v[2:3], v[10:11]
	v_cvt_pk_bf16_f32 v10, v4, v5
	v_pk_mul_f32 v[4:5], v[8:9], v[4:5]
	ds_write_b32 v18, v10 offset:7392
	v_cvt_pk_bf16_f32 v8, v4, v5
	v_lshl_or_b32 v4, v83, 9, v45
	v_ashrrev_i32_e32 v5, 31, v4
	v_cvt_pk_bf16_f32 v10, v2, v3
	v_lshl_add_u64 v[4:5], s[12:13], 0, v[4:5]
	v_pk_mul_f32 v[2:3], v[6:7], v[2:3]
	v_add_u32_e32 v11, 0x9e00, v18
	global_store_dword v[4:5], v8, off nt
	v_cvt_pk_bf16_f32 v9, v2, v3
	v_lshlrev_b32_e32 v2, 16, v19
	v_lshlrev_b32_e32 v3, 16, v25
	v_and_b32_e32 v4, 0xffff, v23
	v_and_b32_e32 v5, 0xffff, v14
	s_movk_i32 s0, 0x80
	ds_write2_b32 v11, v16, v10 offset0:52 offset1:184
	v_and_or_b32 v2, v34, s35, v2
	v_and_or_b32 v3, v27, s35, v3
	v_lshl_or_b32 v4, v21, 16, v4
	v_lshl_or_b32 v5, v9, 16, v5
	v_lshrrev_b32_e32 v6, 16, v34
	v_lshrrev_b32_e32 v7, 16, v27
	v_lshrrev_b32_e32 v8, 16, v23
	v_lshrrev_b32_e32 v10, 16, v14
	v_cmp_gt_u32_e32 vcc, s0, v82
	v_and_or_b32 v6, v19, s88, v6
	v_and_or_b32 v7, v25, s88, v7
	v_and_or_b32 v8, v21, s88, v8
	v_and_or_b32 v9, v9, s88, v10
	global_store_dwordx4 v[28:29], v[2:5], off offset:16
	global_store_dwordx4 v[30:31], v[6:9], off offset:16
	s_and_saveexec_b64 s[12:13], vcc
	s_cbranch_execz .LBB0_288
	v_mul_f32_e32 v0, 0x3fb8aa3b, v0
	v_mul_f32_e32 v1, 0x3fb8aa3b, v1
	v_exp_f32_e32 v0, v0
	v_exp_f32_e32 v1, v1
	v_add_u32_e32 v2, 0x22400, v44
	ds_write_b64 v2, v[0:1]
